# phase 4/5 rebalanced: HGRN-aggregate workgroups arrive on the grid round early and skip the conv rows; the other workgroups take all conv rows (hand-written, 11 rows per wave) while waiting for the ag
# speedup vs baseline: 1.0035x; 1.0035x over previous
; __device__ __forceinline__ unsigned xb_ld(unsigned* p)              { return __hip_atomic_load(p, __ATOMIC_RELAXED, __HIP_MEMORY_SCOPE_AGENT); }
; __device__ __forceinline__ unsigned xb_add(unsigned* p, unsigned v) { return __hip_atomic_fetch_add(p, v, __ATOMIC_RELAXED, __HIP_MEMORY_SCOPE_AGENT); }
; #define XB_SPIN(cond, bar) do { unsigned _sp = 0; while (cond) { __builtin_amdgcn_s_sleep(1); \
;     if ((++_sp & 255u) == 0u) { if (xb_ld(&(bar)[XB_TMO])) break; if (_sp > XB_SPIN_CAP) { atomicAdd(&(bar)[XB_TMO], 1u); break; } } } } while (0)
; __device__ __forceinline__ void xcd_barrier(const XcdBarrier& b) {
;     asm volatile("s_waitcnt vmcnt(0)" ::: "memory");
;     __syncthreads();
;     if (threadIdx.x == 0) {
;         unsigned* bar = b.bar;
;         __builtin_amdgcn_s_waitcnt(0);
;         unsigned nloc = b.st[0], nx = b.st[1];
;         if (nloc == 0u) { xcd_barrier_complete(bar, b.x, nloc, nx); b.st[0] = nloc; b.st[1] = nx; }
;         const unsigned old = xb_add(&bar[XB_XSUB(b.x)], 1u);
;         const unsigned gen = old / nloc;
;         if (old + 1u == (gen + 1u) * nloc) {
;             __builtin_amdgcn_fence(__ATOMIC_RELEASE, "agent");
;             asm volatile("s_waitcnt vmcnt(0)" ::: "memory");
;             const unsigned og = xb_add(&bar[XB_TOP], 1u);
;             const unsigned tg = og / nx;
;             if (og + 1u == (tg + 1u) * nx) xb_add(&bar[XB_TOPGEN], 1u);
;             else XB_SPIN(xb_ld(&bar[XB_TOPGEN]) == tg, bar);
;             __builtin_amdgcn_fence(__ATOMIC_ACQUIRE, "agent");
;             xb_add(&bar[XB_XGEN(b.x)], 1u);
.Lgb3_end:
	s_barrier
	s_add_i32 s100, s100, 1
	s_cmpk_lg_i32 s3, 0x100
	s_cbranch_scc1 .Lgb3_ea_skip
	s_cmpk_lt_u32 s2, 0xc0
	s_cbranch_scc1 .Lgb3_ea_skip
	s_cmp_eq_u64 s[44:45], 0
	s_cbranch_scc1 .Lgb3_ea_skip
	s_mov_b64 s[8:9], exec
	s_mov_b64 exec, s[44:45]
	s_lshl_b32 s10, s33, 8
	s_add_u32 s12, s46, s10
	s_addc_u32 s13, s47, 0
	v_mov_b32_e32 v1, 0x23fc0
	ds_read2_b32 v[2:3], v1 offset1:1
	v_mov_b32_e32 v4, 0x1400
	v_mov_b32_e32 v1, 1
	global_atomic_add v4, v4, v1, s[12:13] sc0
	s_add_i32 s17, s100, 1
	s_waitcnt vmcnt(0) lgkmcnt(0)
	v_readfirstlane_b32 s14, v4
	v_readfirstlane_b32 s15, v2
	s_mul_i32 s18, s17, s15
	s_add_i32 s14, s14, 1
	s_cmp_lg_u32 s14, s18
	s_cbranch_scc1 .Lgb3_ea_done
	buffer_wbl2 sc1
	s_waitcnt vmcnt(0)
	v_mov_b32_e32 v0, 0x10000
	global_atomic_add v0, v1, s[46:47]
	global_atomic_add v0, v1, s[46:47] offset:256
	global_atomic_add v0, v1, s[46:47] offset:512
	global_atomic_add v0, v1, s[46:47] offset:768
	global_atomic_add v0, v1, s[46:47] offset:1024
	global_atomic_add v0, v1, s[46:47] offset:1280
	global_atomic_add v0, v1, s[46:47] offset:1536
	global_atomic_add v0, v1, s[46:47] offset:1792
	global_atomic_add v0, v1, s[46:47] offset:2048
	global_atomic_add v0, v1, s[46:47] offset:2304
	global_atomic_add v0, v1, s[46:47] offset:2560
	global_atomic_add v0, v1, s[46:47] offset:2816
	global_atomic_add v0, v1, s[46:47] offset:3072
	global_atomic_add v0, v1, s[46:47] offset:3328
	global_atomic_add v0, v1, s[46:47] offset:3584
	global_atomic_add v0, v1, s[46:47] offset:3840

; #define LAS __attribute__((address_space(3)))
; __device__ __forceinline__ void hg_a2_quad(unsigned char* ws, float* Gp, LAS unsigned char* lds, int quad, int tid) {
;     const int k = tid & 127, seg = tid >> 7, lane = tid & 63, wave = tid >> 6, l15 = lane & 15, lq = lane >> 4;
;     LAS float* segsum = (LAS float*)lds;
;     LAS float* dl = (LAS float*)(lds + 2048);
;     LAS bf16* KPt = (LAS bf16*)(lds + 2560);
;     LAS bf16* Vt = KPt + 128 * GP;
;     f32x4 R[8];
; #pragma unroll
;     for (int kt = 0; kt < 8; ++kt) R[kt] = (f32x4){0.f, 0.f, 0.f, 0.f};
; #pragma unroll 1
;     for (int gi = 0; gi < 4; ++gi) {
;         const int unit = quad * 4 + gi, bh = unit >> 4, g = unit & 15, b = bh >> 2, h = bh & 3, row0 = b * SEQ + g * 256;
;         const size_t gofs = (size_t)(row0 + seg * 64) * 512 + h * 128 + k;
;         const _Float16* lfp = (const _Float16*)(ws + WS_LF) + gofs; const bf16* vp = (const bf16*)(ws + WS_VV) + gofs;
; __global__ void __launch_bounds__(NT, 2) hymba_fwd(Args args) {
;     ...
;     if (IN(4)) _Pragma("unroll") for (int rep = 0; rep < NREP(4); ++rep) {
;         const int GA = (G * 3) / 4;
;         if (bx < GA) {
;             pg8::Gemm g{XB, (const bf16*)(ws + WS_WIN) + (size_t)2048 * D, M, 1536, D}; pg8::StaticOrder S; S.init(M, 1536, GA, bx);
;             pg8::EpiWin E{(bf16*)(ws + WS_QS), (bf16*)(ws + WS_VV), (bf16*)(ws + WS_GS), (bf16*)(ws + WS_BC), (bf16*)(ws + WS_CU), (_Float16*)(ws + WS_LF), ssq + M, args.in[I_LB], 8};
;             pg8::gemm_phase<pg8::EpiWin, pg8::StaticOrder, true, true>(lds, g, S, E);
;         } else {
;             for (int qd = bx - GA; qd < 64; qd += G - GA) hg_a2_quad(ws, args.out, lds, qd, tid);
.Lgb3_ea_skip:
.LBB0_572:
	s_cmp_lt_i32 s50, 5
	s_cselect_b64 s[6:7], -1, 0
	s_and_b64 s[14:15], s[6:7], s[4:5]
	s_andn2_b64 vcc, exec, s[14:15]
	s_cbranch_vccnz .LBB0_689
	s_mul_i32 s4, s3, 3
	s_ashr_i32 s5, s4, 31
	s_lshr_b32 s5, s5, 30
	s_add_i32 s4, s4, s5
	s_ashr_i32 s25, s4, 2
	s_add_u32 s10, s48, 0x7000000
	s_addc_u32 s11, s49, 0
	s_add_u32 s12, s48, 0x8000000
	s_addc_u32 s13, s49, 0
	s_ashr_i32 s59, s25, 31
	s_waitcnt vmcnt(0)
	v_lshrrev_b32_e32 v0, 1, v209
	s_cmp_ge_i32 s2, s25
	v_and_b32_e32 v43, 15, v209
	v_lshlrev_b32_e32 v44, 2, v209
	v_and_b32_e32 v42, 24, v0
	s_mov_b64 s[4:5], -1
	s_cbranch_scc0 .LBB0_584
	s_sub_i32 s16, s2, s25
	s_cmp_gt_i32 s16, 63
	s_cbranch_scc1 .LBB0_583
	s_load_dwordx2 s[4:5], s[0:1], 0xa8
	v_and_b32_e32 v45, 0x7f, v209
	v_lshrrev_b32_e32 v2, 6, v209
	v_and_b32_e32 v46, 0x1c0, v0
	v_mul_u32_u24_e32 v3, 0x210, v45
	s_add_i32 s17, 0, 0x11200
	v_lshlrev_b32_e32 v0, 1, v46
	v_lshlrev_b32_e32 v32, 13, v2
	v_mov_b32_e32 v33, 0
	v_and_b32_e32 v5, 0xfc, v44
	v_add3_u32 v48, s17, v3, v0
	v_add_u32_e32 v4, 0, v0
	s_waitcnt lgkmcnt(0)
	v_lshl_add_u64 v[0:1], s[4:5], 0, v[32:33]
	v_lshlrev_b32_e32 v32, 2, v5
	v_lshl_add_u64 v[34:35], v[0:1], 0, v[32:33]
	v_lshl_or_b32 v1, v2, 4, v43
	v_mul_u32_u24_e32 v1, 0x210, v1
	v_lshlrev_b32_e32 v2, 1, v42
	s_add_u32 s18, s48, 0x80000
	v_add3_u32 v50, s17, v1, v2
	v_mul_u32_u24_e32 v1, 0x210, v43
	s_addc_u32 s19, s49, 0
	v_add3_u32 v51, 0, v2, v1
	v_lshl_add_u32 v1, s2, 9, v209
	s_lshl_b32 s17, s25, 9
	s_lshl_b32 s20, s3, 9
	v_subrev_u32_e32 v52, s17, v1
	s_sub_i32 s27, s20, s17
	s_lshl_b32 s17, s2, 2
	s_lshl_b32 s20, s25, 2
	s_sub_i32 s28, s17, s20
	s_lshl_b32 s17, s3, 2
	s_sub_i32 s29, s17, s20
	s_lshl_b32 s17, s2, 10
	s_lshl_b32 s20, s25, 10
	s_movk_i32 s4, 0x80
	s_movk_i32 s6, 0xff
	s_movk_i32 s8, 0x17f
	v_and_b32_e32 v0, 48, v209
	s_sub_i32 s30, s17, s20
	s_lshl_b32 s17, s3, 10
	v_lshl_add_u32 v47, v209, 2, 0
	v_lshl_add_u32 v49, v45, 2, 0
	v_cmp_gt_u32_e64 s[4:5], s4, v209
	v_cmp_lt_u32_e64 s[6:7], s6, v209
	v_cmp_lt_u32_e64 s[8:9], s8, v209
	s_sub_i32 s26, s3, s25
	s_sub_i32 s31, s17, s20
	s_movk_i32 s34, 0x1000
	s_movk_i32 s35, 0x2000
	s_movk_i32 s36, 0x3000
	s_movk_i32 s37, 0x4000
	s_movk_i32 s38, 0x5000
	s_movk_i32 s39, 0x6000
	s_movk_i32 s40, 0x7000
	s_mov_b32 s41, 0x8000
	s_mov_b32 s42, 0x9000
	s_mov_b32 s43, 0xa000
	s_mov_b32 s61, 0xb000
	s_mov_b32 s62, 0xc000
	s_mov_b32 s63, 0xd000
	s_mov_b32 s64, 0xe000
	s_mov_b32 s65, 0xf000
	v_add_u32_e32 v53, v4, v3
	v_add_u32_e32 v54, 0, v0
	s_mov_b64 s[20:21], 0x1000000
	s_branch .LBB0_577

; #define LAS __attribute__((address_space(3)))
; __device__ __forceinline__ unsigned xb_ld(unsigned* p)              { return __hip_atomic_load(p, __ATOMIC_RELAXED, __HIP_MEMORY_SCOPE_AGENT); }
; __device__ __forceinline__ unsigned xb_add(unsigned* p, unsigned v) { return __hip_atomic_fetch_add(p, v, __ATOMIC_RELAXED, __HIP_MEMORY_SCOPE_AGENT); }
; #define XB_SPIN(cond, bar) do { unsigned _sp = 0; while (cond) { __builtin_amdgcn_s_sleep(1); \
;     if ((++_sp & 255u) == 0u) { if (xb_ld(&(bar)[XB_TMO])) break; if (_sp > XB_SPIN_CAP) { atomicAdd(&(bar)[XB_TMO], 1u); break; } } } } while (0)
; #define SEAM(k) do { if (IN(k) && IN((k) + 1)) flat_barrier((unsigned*)(ws + WS_BAR + 65536), fgen, (unsigned)G); } while (0)
; __device__ __forceinline__ void xcd_barrier(const XcdBarrier& b) {
;     asm volatile("s_waitcnt vmcnt(0)" ::: "memory");
;     __syncthreads();
;     if (threadIdx.x == 0) {
;         unsigned* bar = b.bar;
;         __builtin_amdgcn_s_waitcnt(0);
;         unsigned nloc = b.st[0], nx = b.st[1];
;         if (nloc == 0u) { xcd_barrier_complete(bar, b.x, nloc, nx); b.st[0] = nloc; b.st[1] = nx; }
;         const unsigned old = xb_add(&bar[XB_XSUB(b.x)], 1u);
;         const unsigned gen = old / nloc;
;         if (old + 1u == (gen + 1u) * nloc) {
;             __builtin_amdgcn_fence(__ATOMIC_RELEASE, "agent");
;             asm volatile("s_waitcnt vmcnt(0)" ::: "memory");
;             const unsigned og = xb_add(&bar[XB_TOP], 1u);
;             const unsigned tg = og / nx;
;             if (og + 1u == (tg + 1u) * nx) xb_add(&bar[XB_TOPGEN], 1u);
;             else XB_SPIN(xb_ld(&bar[XB_TOPGEN]) == tg, bar);
;             __builtin_amdgcn_fence(__ATOMIC_ACQUIRE, "agent");
;             xb_add(&bar[XB_XGEN(b.x)], 1u);
;             asm volatile("s_waitcnt vmcnt(0)" ::: "memory");
;         } else {
;             XB_SPIN(xb_ld(&bar[XB_XGEN(b.x)]) == gen, bar);
;             __builtin_amdgcn_fence(__ATOMIC_ACQUIRE, "agent");
;             asm volatile("s_waitcnt vmcnt(0)" ::: "memory");
;         }
;     }
;     __syncthreads();
; }
; __global__ void __launch_bounds__(NT, 2) hymba_fwd(Args args) {
;     ...
;     if (IN(4)) p0_items(args, (LAS float*)(lds + wave * 16384), P0_MID, P0_GU2, gw, NGW, lane);
;     SEAM(4);
;     if (IN(5)) _Pragma("unroll") for (int rep = 0; rep < NREP(5); ++rep) {
.LBB0_689:
	s_cmp_gt_i32 s51, 5
	s_cselect_b64 s[4:5], -1, 0
	s_and_b64 s[6:7], s[14:15], s[4:5]
	s_andn2_b64 vcc, exec, s[6:7]
	s_cbranch_vccnz .LBB0_743
	s_cmpk_lg_i32 s3, 0x100
	s_cbranch_scc1 .Lgb4_all
	s_cmpk_lt_u32 s2, 0xc0
	s_cbranch_scc1 .Lgb4_all
	s_waitcnt vmcnt(0) lgkmcnt(0)
	s_barrier
	s_cmp_eq_u64 s[44:45], 0
	s_cbranch_scc1 .Lgb4_hend
	s_mov_b64 s[8:9], exec
	s_mov_b64 exec, s[44:45]
	v_mov_b32_e32 v0, 0x8900
	v_mov_b32_e32 v1, 1
	global_atomic_add v0, v1, s[46:47]
	s_mov_b32 s19, 0
.Lgb4_hgpoll:
	global_load_dword v4, v0, s[46:47] sc1
	s_waitcnt vmcnt(0)
	v_readfirstlane_b32 s14, v4
	s_cmp_ge_u32 s14, 64
	s_cbranch_scc1 .Lgb4_hacq
	s_sleep 1
	s_add_i32 s19, s19, 1
	s_cmp_lt_u32 s19, 20000
	s_cbranch_scc1 .Lgb4_hgpoll

; template <int NR>
; __device__ __forceinline__ void conv_rows(const Args& a, int r0, int rstride, int lane) {
;     unsigned char* ws = a.ws; const int c0 = 8 * lane;
;     const bf16* BCp = (const bf16*)(ws + WS_BC); const bf16* CUp = (const bf16*)(ws + WS_CU);
;     v4u bq[NR], u0[NR], u1[NR], u2[NR];
; #pragma unroll
;     for (int i = 0; i < NR; ++i) { const int row = r0 + i * rstride, t = row & (SEQ - 1);
;         bq[i] = *(const v4u*)(BCp + (size_t)row * 512 + c0); u0[i] = *(const v4u*)(CUp + (size_t)row * 512 + c0);
;         u1[i] = (v4u){0, 0, 0, 0}; u2[i] = (v4u){0, 0, 0, 0};
;         if (t >= 1) u1[i] = *(const v4u*)(CUp + (size_t)(row - 1) * 512 + c0);
;         if (t >= 2) u2[i] = *(const v4u*)(CUp + (size_t)(row - 2) * 512 + c0); }
;     const float* cw = a.in[I_CONVW] + c0; const float* gn = a.in[I_CONVN] + c0;
;     const f32x4 w0a = *(const f32x4*)(cw), w0b = *(const f32x4*)(cw + 4), w1a = *(const f32x4*)(cw + 512), w1b = *(const f32x4*)(cw + 516), w2a = *(const f32x4*)(cw + 1024), w2b = *(const f32x4*)(cw + 1028);
;     const f32x4 ga = *(const f32x4*)(gn), gb = *(const f32x4*)(gn + 4);
; #pragma unroll
; __global__ void __launch_bounds__(NT, 2) hymba_fwd(Args args) {
;     ...
;     if (IN(5)) _Pragma("unroll") for (int rep = 0; rep < NREP(5); ++rep) {
;         if (M % (4 * NGW) == 0) { for (int r = gw; r < M; r += 4 * NGW) conv_rows<4>(args, r, NGW, lane); } else { for (int r = gw; r < M; r += NGW) conv_rows<1>(args, r, NGW, lane); }
.Lgb4_after:
.LBB0_743:
	s_cmp_lt_i32 s50, 6
	s_cselect_b64 s[6:7], -1, 0
	s_and_b64 s[62:63], s[6:7], s[4:5]
	s_andn2_b64 vcc, exec, s[62:63]
	s_cbranch_vccnz .LBB0_939
	s_cmpk_lg_i32 s3, 0x100
	s_cbranch_scc1 .Lc5_generic
	s_cmpk_lt_u32 s2, 0xc0
	s_cbranch_scc1 .Lc5_rows
	s_load_dwordx4 s[16:19], s[0:1], 0xa8
	s_load_dwordx4 s[12:15], s[0:1], 0x40
	v_lshlrev_b32_e32 v96, 4, v208
	v_mov_b32_e32 v97, 0
	s_waitcnt vmcnt(0) lgkmcnt(0)
	s_branch .LBB0_776
.Lc5_rows:
	s_load_dwordx4 s[16:19], s[0:1], 0xa8
	s_load_dwordx4 s[12:15], s[0:1], 0x40
	s_load_dwordx2 s[8:9], s[0:1], 0x50
	s_lshl_b32 s24, s2, 3
	s_add_i32 s24, s24, s88
	v_lshlrev_b32_e32 v0, 4, v208
	v_lshlrev_b32_e32 v1, 5, v208
	s_waitcnt vmcnt(0) lgkmcnt(0)
	s_add_u32 s20, s18, 0xa000000
	s_addc_u32 s21, s19, 0
	s_add_u32 s22, s18, 0xb000000
	s_addc_u32 s23, s19, 0
	s_add_u32 s26, s18, 0xe000000
	s_addc_u32 s27, s19, 0
	global_load_dwordx4 v[2:5], v1, s[14:15]
	global_load_dwordx4 v[6:9], v1, s[14:15] offset:16
	global_load_dwordx4 v[10:13], v1, s[14:15] offset:2048
	global_load_dwordx4 v[14:17], v1, s[14:15] offset:2064
	s_add_u32 s4, s14, 0x1000
	s_addc_u32 s5, s15, 0
	global_load_dwordx4 v[18:21], v1, s[4:5]
	global_load_dwordx4 v[22:25], v1, s[4:5] offset:16
	global_load_dwordx4 v[26:29], v1, s[8:9]
	global_load_dwordx4 v[30:33], v1, s[8:9] offset:16
	s_add_i32 s10, s24, 0x0
	s_lshl_b32 s11, s10, 10
	s_add_u32 s4, s20, s11
	s_addc_u32 s5, s21, 0
	s_add_u32 s6, s22, s11
	s_addc_u32 s7, s23, 0
	global_load_dwordx4 v[40:43], v0, s[4:5]
	global_load_dwordx4 v[44:47], v0, s[6:7]
	global_load_dwordx4 v[48:51], v0, s[6:7] offset:-1024
	global_load_dwordx4 v[52:55], v0, s[6:7] offset:-2048
	s_add_i32 s10, s24, 0x600
	s_lshl_b32 s11, s10, 10
	s_add_u32 s4, s20, s11
	s_addc_u32 s5, s21, 0
	s_add_u32 s6, s22, s11
	s_addc_u32 s7, s23, 0
	global_load_dwordx4 v[56:59], v0, s[4:5]
	global_load_dwordx4 v[60:63], v0, s[6:7]
	global_load_dwordx4 v[64:67], v0, s[6:7] offset:-1024
	global_load_dwordx4 v[68:71], v0, s[6:7] offset:-2048
	s_add_i32 s10, s24, 0xc00
	s_lshl_b32 s11, s10, 10
	s_add_u32 s4, s20, s11
	s_addc_u32 s5, s21, 0
	s_add_u32 s6, s22, s11
	s_addc_u32 s7, s23, 0
	global_load_dwordx4 v[72:75], v0, s[4:5]
	global_load_dwordx4 v[76:79], v0, s[6:7]
	global_load_dwordx4 v[80:83], v0, s[6:7] offset:-1024
	global_load_dwordx4 v[84:87], v0, s[6:7] offset:-2048
	s_add_i32 s10, s24, 0x1200
	s_lshl_b32 s11, s10, 10
	s_add_u32 s4, s20, s11
	s_addc_u32 s5, s21, 0
	s_add_u32 s6, s22, s11
	s_addc_u32 s7, s23, 0
	global_load_dwordx4 v[88:91], v0, s[4:5]
	global_load_dwordx4 v[92:95], v0, s[6:7]
	global_load_dwordx4 v[96:99], v0, s[6:7] offset:-1024
	global_load_dwordx4 v[100:103], v0, s[6:7] offset:-2048
	s_add_i32 s10, s24, 0x1800
	s_lshl_b32 s11, s10, 10
	s_add_u32 s4, s20, s11
	s_addc_u32 s5, s21, 0
	s_add_u32 s6, s22, s11
	s_addc_u32 s7, s23, 0
	global_load_dwordx4 v[104:107], v0, s[4:5]
	global_load_dwordx4 v[108:111], v0, s[6:7]
	global_load_dwordx4 v[112:115], v0, s[6:7] offset:-1024
	global_load_dwordx4 v[116:119], v0, s[6:7] offset:-2048
	s_add_i32 s10, s24, 0x1e00
	s_lshl_b32 s11, s10, 10
	s_add_u32 s4, s20, s11
	s_addc_u32 s5, s21, 0
	s_add_u32 s6, s22, s11
	s_addc_u32 s7, s23, 0
	global_load_dwordx4 v[120:123], v0, s[4:5]
	global_load_dwordx4 v[124:127], v0, s[6:7]
	global_load_dwordx4 v[128:131], v0, s[6:7] offset:-1024
	global_load_dwordx4 v[132:135], v0, s[6:7] offset:-2048
	s_waitcnt vmcnt(20)
	s_add_i32 s10, s24, 0x0
	s_and_b32 s11, s10, 0xfff
	s_cmp_lg_u32 s11, 0
	s_cbranch_scc1 .Lc5_k1_0
	v_mov_b32_e32 v48, 0
	v_mov_b32_e32 v49, 0
	v_mov_b32_e32 v50, 0
	v_mov_b32_e32 v51, 0

; template <int NR>
; __device__ __forceinline__ void conv_rows(const Args& a, int r0, int rstride, int lane) {
;     ...
;     for (int i = 0; i < NR; ++i) { const int row = r0 + i * rstride; float y[8]; float s = 0.f;
; #pragma unroll
;         for (int j = 0; j < 8; ++j) { const int sh = (j & 1) * 16; const unsigned ub = bq[i][j >> 1], x0 = u0[i][j >> 1], x1 = u1[i][j >> 1], x2 = u2[i][j >> 1];
;             const float B = __uint_as_float(((ub >> sh) & 0xffffu) << 16), c_0 = __uint_as_float(((x0 >> sh) & 0xffffu) << 16), c_1 = __uint_as_float(((x1 >> sh) & 0xffffu) << 16), c_2 = __uint_as_float(((x2 >> sh) & 0xffffu) << 16);
;             const float k0 = j < 4 ? w0a[j & 3] : w0b[j & 3], k1 = j < 4 ? w1a[j & 3] : w1b[j & 3], k2 = j < 4 ? w2a[j & 3] : w2b[j & 3];
;             y[j] = B * (k0 * c_2 + k1 * c_1 + k2 * c_0); s += y[j] * y[j]; }
.Lc5_k2_0:
	v_lshlrev_b32_e32 v184, 16, v52
	v_and_b32_e32 v185, 0xffff0000, v52
	v_lshlrev_b32_e32 v186, 16, v48
	v_and_b32_e32 v187, 0xffff0000, v48
	v_lshlrev_b32_e32 v188, 16, v44
	v_and_b32_e32 v189, 0xffff0000, v44
	v_lshlrev_b32_e32 v190, 16, v40
	v_and_b32_e32 v191, 0xffff0000, v40
	v_pk_mul_f32 v[192:193], v[2:3], v[184:185]
	v_pk_fma_f32 v[192:193], v[10:11], v[186:187], v[192:193]
	v_pk_fma_f32 v[192:193], v[18:19], v[188:189], v[192:193]
	v_pk_mul_f32 v[136:137], v[192:193], v[190:191]
	v_pk_mul_f32 v[194:195], v[136:137], v[136:137]
	v_lshlrev_b32_e32 v184, 16, v53
	v_and_b32_e32 v185, 0xffff0000, v53
	v_lshlrev_b32_e32 v186, 16, v49
	v_and_b32_e32 v187, 0xffff0000, v49
	v_lshlrev_b32_e32 v188, 16, v45
	v_and_b32_e32 v189, 0xffff0000, v45
	v_lshlrev_b32_e32 v190, 16, v41
	v_and_b32_e32 v191, 0xffff0000, v41
	v_pk_mul_f32 v[192:193], v[4:5], v[184:185]
	v_pk_fma_f32 v[192:193], v[12:13], v[186:187], v[192:193]
	v_pk_fma_f32 v[192:193], v[20:21], v[188:189], v[192:193]
	v_pk_mul_f32 v[138:139], v[192:193], v[190:191]
	v_pk_fma_f32 v[194:195], v[138:139], v[138:139], v[194:195]
	v_lshlrev_b32_e32 v184, 16, v54
	v_and_b32_e32 v185, 0xffff0000, v54
	v_lshlrev_b32_e32 v186, 16, v50
	v_and_b32_e32 v187, 0xffff0000, v50
	v_lshlrev_b32_e32 v188, 16, v46
	v_and_b32_e32 v189, 0xffff0000, v46
	v_lshlrev_b32_e32 v190, 16, v42
	v_and_b32_e32 v191, 0xffff0000, v42
	v_pk_mul_f32 v[192:193], v[6:7], v[184:185]
	v_pk_fma_f32 v[192:193], v[14:15], v[186:187], v[192:193]
	v_pk_fma_f32 v[192:193], v[22:23], v[188:189], v[192:193]
	v_pk_mul_f32 v[140:141], v[192:193], v[190:191]
	v_pk_fma_f32 v[194:195], v[140:141], v[140:141], v[194:195]
	v_lshlrev_b32_e32 v184, 16, v55
	v_and_b32_e32 v185, 0xffff0000, v55
	v_lshlrev_b32_e32 v186, 16, v51
	v_and_b32_e32 v187, 0xffff0000, v51
	v_lshlrev_b32_e32 v188, 16, v47
	v_and_b32_e32 v189, 0xffff0000, v47
	v_lshlrev_b32_e32 v190, 16, v43
	v_and_b32_e32 v191, 0xffff0000, v43
	v_pk_mul_f32 v[192:193], v[8:9], v[184:185]
	v_pk_fma_f32 v[192:193], v[16:17], v[186:187], v[192:193]
	v_pk_fma_f32 v[192:193], v[24:25], v[188:189], v[192:193]
	v_pk_mul_f32 v[142:143], v[192:193], v[190:191]
	v_pk_fma_f32 v[194:195], v[142:143], v[142:143], v[194:195]
	v_add_f32_e32 v40, v194, v195
	s_waitcnt vmcnt(16)
	s_add_i32 s10, s24, 0x600
	s_and_b32 s11, s10, 0xfff
	s_cmp_lg_u32 s11, 0
	s_cbranch_scc1 .Lc5_k1_1
	v_mov_b32_e32 v64, 0
	v_mov_b32_e32 v65, 0
	v_mov_b32_e32 v66, 0
	v_mov_b32_e32 v67, 0

; template <int NR>
; __device__ __forceinline__ void conv_rows(const Args& a, int r0, int rstride, int lane) {
;     ...
;     for (int i = 0; i < NR; ++i) { const int row = r0 + i * rstride; float y[8]; float s = 0.f;
; #pragma unroll
;         for (int j = 0; j < 8; ++j) { const int sh = (j & 1) * 16; const unsigned ub = bq[i][j >> 1], x0 = u0[i][j >> 1], x1 = u1[i][j >> 1], x2 = u2[i][j >> 1];
;             const float B = __uint_as_float(((ub >> sh) & 0xffffu) << 16), c_0 = __uint_as_float(((x0 >> sh) & 0xffffu) << 16), c_1 = __uint_as_float(((x1 >> sh) & 0xffffu) << 16), c_2 = __uint_as_float(((x2 >> sh) & 0xffffu) << 16);
;             const float k0 = j < 4 ? w0a[j & 3] : w0b[j & 3], k1 = j < 4 ? w1a[j & 3] : w1b[j & 3], k2 = j < 4 ? w2a[j & 3] : w2b[j & 3];
;             y[j] = B * (k0 * c_2 + k1 * c_1 + k2 * c_0); s += y[j] * y[j]; }
.Lc5_k2_1:
	v_lshlrev_b32_e32 v184, 16, v68
	v_and_b32_e32 v185, 0xffff0000, v68
	v_lshlrev_b32_e32 v186, 16, v64
	v_and_b32_e32 v187, 0xffff0000, v64
	v_lshlrev_b32_e32 v188, 16, v60
	v_and_b32_e32 v189, 0xffff0000, v60
	v_lshlrev_b32_e32 v190, 16, v56
	v_and_b32_e32 v191, 0xffff0000, v56
	v_pk_mul_f32 v[192:193], v[2:3], v[184:185]
	v_pk_fma_f32 v[192:193], v[10:11], v[186:187], v[192:193]
	v_pk_fma_f32 v[192:193], v[18:19], v[188:189], v[192:193]
	v_pk_mul_f32 v[144:145], v[192:193], v[190:191]
	v_pk_mul_f32 v[194:195], v[144:145], v[144:145]
	v_lshlrev_b32_e32 v184, 16, v69
	v_and_b32_e32 v185, 0xffff0000, v69
	v_lshlrev_b32_e32 v186, 16, v65
	v_and_b32_e32 v187, 0xffff0000, v65
	v_lshlrev_b32_e32 v188, 16, v61
	v_and_b32_e32 v189, 0xffff0000, v61
	v_lshlrev_b32_e32 v190, 16, v57
	v_and_b32_e32 v191, 0xffff0000, v57
	v_pk_mul_f32 v[192:193], v[4:5], v[184:185]
	v_pk_fma_f32 v[192:193], v[12:13], v[186:187], v[192:193]
	v_pk_fma_f32 v[192:193], v[20:21], v[188:189], v[192:193]
	v_pk_mul_f32 v[146:147], v[192:193], v[190:191]
	v_pk_fma_f32 v[194:195], v[146:147], v[146:147], v[194:195]
	v_lshlrev_b32_e32 v184, 16, v70
	v_and_b32_e32 v185, 0xffff0000, v70
	v_lshlrev_b32_e32 v186, 16, v66
	v_and_b32_e32 v187, 0xffff0000, v66
	v_lshlrev_b32_e32 v188, 16, v62
	v_and_b32_e32 v189, 0xffff0000, v62
	v_lshlrev_b32_e32 v190, 16, v58
	v_and_b32_e32 v191, 0xffff0000, v58
	v_pk_mul_f32 v[192:193], v[6:7], v[184:185]
	v_pk_fma_f32 v[192:193], v[14:15], v[186:187], v[192:193]
	v_pk_fma_f32 v[192:193], v[22:23], v[188:189], v[192:193]
	v_pk_mul_f32 v[148:149], v[192:193], v[190:191]
	v_pk_fma_f32 v[194:195], v[148:149], v[148:149], v[194:195]
	v_lshlrev_b32_e32 v184, 16, v71
	v_and_b32_e32 v185, 0xffff0000, v71
	v_lshlrev_b32_e32 v186, 16, v67
	v_and_b32_e32 v187, 0xffff0000, v67
	v_lshlrev_b32_e32 v188, 16, v63
	v_and_b32_e32 v189, 0xffff0000, v63
	v_lshlrev_b32_e32 v190, 16, v59
	v_and_b32_e32 v191, 0xffff0000, v59
	v_pk_mul_f32 v[192:193], v[8:9], v[184:185]
	v_pk_fma_f32 v[192:193], v[16:17], v[186:187], v[192:193]
	v_pk_fma_f32 v[192:193], v[24:25], v[188:189], v[192:193]
	v_pk_mul_f32 v[150:151], v[192:193], v[190:191]
	v_pk_fma_f32 v[194:195], v[150:151], v[150:151], v[194:195]
	v_add_f32_e32 v42, v194, v195
	s_waitcnt vmcnt(12)
	s_add_i32 s10, s24, 0xc00
	s_and_b32 s11, s10, 0xfff
	s_cmp_lg_u32 s11, 0
	s_cbranch_scc1 .Lc5_k1_2
	v_mov_b32_e32 v80, 0
	v_mov_b32_e32 v81, 0
	v_mov_b32_e32 v82, 0
	v_mov_b32_e32 v83, 0

; template <int NR>
; __device__ __forceinline__ void conv_rows(const Args& a, int r0, int rstride, int lane) {
;     ...
;     for (int i = 0; i < NR; ++i) { const int row = r0 + i * rstride; float y[8]; float s = 0.f;
; #pragma unroll
;         for (int j = 0; j < 8; ++j) { const int sh = (j & 1) * 16; const unsigned ub = bq[i][j >> 1], x0 = u0[i][j >> 1], x1 = u1[i][j >> 1], x2 = u2[i][j >> 1];
;             const float B = __uint_as_float(((ub >> sh) & 0xffffu) << 16), c_0 = __uint_as_float(((x0 >> sh) & 0xffffu) << 16), c_1 = __uint_as_float(((x1 >> sh) & 0xffffu) << 16), c_2 = __uint_as_float(((x2 >> sh) & 0xffffu) << 16);
;             const float k0 = j < 4 ? w0a[j & 3] : w0b[j & 3], k1 = j < 4 ? w1a[j & 3] : w1b[j & 3], k2 = j < 4 ? w2a[j & 3] : w2b[j & 3];
;             y[j] = B * (k0 * c_2 + k1 * c_1 + k2 * c_0); s += y[j] * y[j]; }
.Lc5_k2_2:
	v_lshlrev_b32_e32 v184, 16, v84
	v_and_b32_e32 v185, 0xffff0000, v84
	v_lshlrev_b32_e32 v186, 16, v80
	v_and_b32_e32 v187, 0xffff0000, v80
	v_lshlrev_b32_e32 v188, 16, v76
	v_and_b32_e32 v189, 0xffff0000, v76
	v_lshlrev_b32_e32 v190, 16, v72
	v_and_b32_e32 v191, 0xffff0000, v72
	v_pk_mul_f32 v[192:193], v[2:3], v[184:185]
	v_pk_fma_f32 v[192:193], v[10:11], v[186:187], v[192:193]
	v_pk_fma_f32 v[192:193], v[18:19], v[188:189], v[192:193]
	v_pk_mul_f32 v[152:153], v[192:193], v[190:191]
	v_pk_mul_f32 v[194:195], v[152:153], v[152:153]
	v_lshlrev_b32_e32 v184, 16, v85
	v_and_b32_e32 v185, 0xffff0000, v85
	v_lshlrev_b32_e32 v186, 16, v81
	v_and_b32_e32 v187, 0xffff0000, v81
	v_lshlrev_b32_e32 v188, 16, v77
	v_and_b32_e32 v189, 0xffff0000, v77
	v_lshlrev_b32_e32 v190, 16, v73
	v_and_b32_e32 v191, 0xffff0000, v73
	v_pk_mul_f32 v[192:193], v[4:5], v[184:185]
	v_pk_fma_f32 v[192:193], v[12:13], v[186:187], v[192:193]
	v_pk_fma_f32 v[192:193], v[20:21], v[188:189], v[192:193]
	v_pk_mul_f32 v[154:155], v[192:193], v[190:191]
	v_pk_fma_f32 v[194:195], v[154:155], v[154:155], v[194:195]
	v_lshlrev_b32_e32 v184, 16, v86
	v_and_b32_e32 v185, 0xffff0000, v86
	v_lshlrev_b32_e32 v186, 16, v82
	v_and_b32_e32 v187, 0xffff0000, v82
	v_lshlrev_b32_e32 v188, 16, v78
	v_and_b32_e32 v189, 0xffff0000, v78
	v_lshlrev_b32_e32 v190, 16, v74
	v_and_b32_e32 v191, 0xffff0000, v74
	v_pk_mul_f32 v[192:193], v[6:7], v[184:185]
	v_pk_fma_f32 v[192:193], v[14:15], v[186:187], v[192:193]
	v_pk_fma_f32 v[192:193], v[22:23], v[188:189], v[192:193]
	v_pk_mul_f32 v[156:157], v[192:193], v[190:191]
	v_pk_fma_f32 v[194:195], v[156:157], v[156:157], v[194:195]
	v_lshlrev_b32_e32 v184, 16, v87
	v_and_b32_e32 v185, 0xffff0000, v87
	v_lshlrev_b32_e32 v186, 16, v83
	v_and_b32_e32 v187, 0xffff0000, v83
	v_lshlrev_b32_e32 v188, 16, v79
	v_and_b32_e32 v189, 0xffff0000, v79
	v_lshlrev_b32_e32 v190, 16, v75
	v_and_b32_e32 v191, 0xffff0000, v75
	v_pk_mul_f32 v[192:193], v[8:9], v[184:185]
	v_pk_fma_f32 v[192:193], v[16:17], v[186:187], v[192:193]
	v_pk_fma_f32 v[192:193], v[24:25], v[188:189], v[192:193]
	v_pk_mul_f32 v[158:159], v[192:193], v[190:191]
	v_pk_fma_f32 v[194:195], v[158:159], v[158:159], v[194:195]
	v_add_f32_e32 v44, v194, v195
	s_waitcnt vmcnt(8)
	s_add_i32 s10, s24, 0x1200
	s_and_b32 s11, s10, 0xfff
	s_cmp_lg_u32 s11, 0
	s_cbranch_scc1 .Lc5_k1_3
	v_mov_b32_e32 v96, 0
	v_mov_b32_e32 v97, 0
	v_mov_b32_e32 v98, 0
	v_mov_b32_e32 v99, 0

; template <int NR>
; __device__ __forceinline__ void conv_rows(const Args& a, int r0, int rstride, int lane) {
;     ...
;     for (int i = 0; i < NR; ++i) { const int row = r0 + i * rstride; float y[8]; float s = 0.f;
; #pragma unroll
;         for (int j = 0; j < 8; ++j) { const int sh = (j & 1) * 16; const unsigned ub = bq[i][j >> 1], x0 = u0[i][j >> 1], x1 = u1[i][j >> 1], x2 = u2[i][j >> 1];
;             const float B = __uint_as_float(((ub >> sh) & 0xffffu) << 16), c_0 = __uint_as_float(((x0 >> sh) & 0xffffu) << 16), c_1 = __uint_as_float(((x1 >> sh) & 0xffffu) << 16), c_2 = __uint_as_float(((x2 >> sh) & 0xffffu) << 16);
;             const float k0 = j < 4 ? w0a[j & 3] : w0b[j & 3], k1 = j < 4 ? w1a[j & 3] : w1b[j & 3], k2 = j < 4 ? w2a[j & 3] : w2b[j & 3];
;             y[j] = B * (k0 * c_2 + k1 * c_1 + k2 * c_0); s += y[j] * y[j]; }
.Lc5_k2_3:
	v_lshlrev_b32_e32 v184, 16, v100
	v_and_b32_e32 v185, 0xffff0000, v100
	v_lshlrev_b32_e32 v186, 16, v96
	v_and_b32_e32 v187, 0xffff0000, v96
	v_lshlrev_b32_e32 v188, 16, v92
	v_and_b32_e32 v189, 0xffff0000, v92
	v_lshlrev_b32_e32 v190, 16, v88
	v_and_b32_e32 v191, 0xffff0000, v88
	v_pk_mul_f32 v[192:193], v[2:3], v[184:185]
	v_pk_fma_f32 v[192:193], v[10:11], v[186:187], v[192:193]
	v_pk_fma_f32 v[192:193], v[18:19], v[188:189], v[192:193]
	v_pk_mul_f32 v[160:161], v[192:193], v[190:191]
	v_pk_mul_f32 v[194:195], v[160:161], v[160:161]
	v_lshlrev_b32_e32 v184, 16, v101
	v_and_b32_e32 v185, 0xffff0000, v101
	v_lshlrev_b32_e32 v186, 16, v97
	v_and_b32_e32 v187, 0xffff0000, v97
	v_lshlrev_b32_e32 v188, 16, v93
	v_and_b32_e32 v189, 0xffff0000, v93
	v_lshlrev_b32_e32 v190, 16, v89
	v_and_b32_e32 v191, 0xffff0000, v89
	v_pk_mul_f32 v[192:193], v[4:5], v[184:185]
	v_pk_fma_f32 v[192:193], v[12:13], v[186:187], v[192:193]
	v_pk_fma_f32 v[192:193], v[20:21], v[188:189], v[192:193]
	v_pk_mul_f32 v[162:163], v[192:193], v[190:191]
	v_pk_fma_f32 v[194:195], v[162:163], v[162:163], v[194:195]
	v_lshlrev_b32_e32 v184, 16, v102
	v_and_b32_e32 v185, 0xffff0000, v102
	v_lshlrev_b32_e32 v186, 16, v98
	v_and_b32_e32 v187, 0xffff0000, v98
	v_lshlrev_b32_e32 v188, 16, v94
	v_and_b32_e32 v189, 0xffff0000, v94
	v_lshlrev_b32_e32 v190, 16, v90
	v_and_b32_e32 v191, 0xffff0000, v90
	v_pk_mul_f32 v[192:193], v[6:7], v[184:185]
	v_pk_fma_f32 v[192:193], v[14:15], v[186:187], v[192:193]
	v_pk_fma_f32 v[192:193], v[22:23], v[188:189], v[192:193]
	v_pk_mul_f32 v[164:165], v[192:193], v[190:191]
	v_pk_fma_f32 v[194:195], v[164:165], v[164:165], v[194:195]
	v_lshlrev_b32_e32 v184, 16, v103
	v_and_b32_e32 v185, 0xffff0000, v103
	v_lshlrev_b32_e32 v186, 16, v99
	v_and_b32_e32 v187, 0xffff0000, v99
	v_lshlrev_b32_e32 v188, 16, v95
	v_and_b32_e32 v189, 0xffff0000, v95
	v_lshlrev_b32_e32 v190, 16, v91
	v_and_b32_e32 v191, 0xffff0000, v91
	v_pk_mul_f32 v[192:193], v[8:9], v[184:185]
	v_pk_fma_f32 v[192:193], v[16:17], v[186:187], v[192:193]
	v_pk_fma_f32 v[192:193], v[24:25], v[188:189], v[192:193]
	v_pk_mul_f32 v[166:167], v[192:193], v[190:191]
	v_pk_fma_f32 v[194:195], v[166:167], v[166:167], v[194:195]
	v_add_f32_e32 v46, v194, v195
	s_waitcnt vmcnt(4)
	s_add_i32 s10, s24, 0x1800
	s_and_b32 s11, s10, 0xfff
	s_cmp_lg_u32 s11, 0
	s_cbranch_scc1 .Lc5_k1_4
	v_mov_b32_e32 v112, 0
	v_mov_b32_e32 v113, 0
	v_mov_b32_e32 v114, 0
	v_mov_b32_e32 v115, 0

; template <int NR>
; __device__ __forceinline__ void conv_rows(const Args& a, int r0, int rstride, int lane) {
;     ...
;     for (int i = 0; i < NR; ++i) { const int row = r0 + i * rstride; float y[8]; float s = 0.f;
; #pragma unroll
;         for (int j = 0; j < 8; ++j) { const int sh = (j & 1) * 16; const unsigned ub = bq[i][j >> 1], x0 = u0[i][j >> 1], x1 = u1[i][j >> 1], x2 = u2[i][j >> 1];
;             const float B = __uint_as_float(((ub >> sh) & 0xffffu) << 16), c_0 = __uint_as_float(((x0 >> sh) & 0xffffu) << 16), c_1 = __uint_as_float(((x1 >> sh) & 0xffffu) << 16), c_2 = __uint_as_float(((x2 >> sh) & 0xffffu) << 16);
;             const float k0 = j < 4 ? w0a[j & 3] : w0b[j & 3], k1 = j < 4 ? w1a[j & 3] : w1b[j & 3], k2 = j < 4 ? w2a[j & 3] : w2b[j & 3];
;             y[j] = B * (k0 * c_2 + k1 * c_1 + k2 * c_0); s += y[j] * y[j]; }
.Lc5_k2_4:
	v_lshlrev_b32_e32 v184, 16, v116
	v_and_b32_e32 v185, 0xffff0000, v116
	v_lshlrev_b32_e32 v186, 16, v112
	v_and_b32_e32 v187, 0xffff0000, v112
	v_lshlrev_b32_e32 v188, 16, v108
	v_and_b32_e32 v189, 0xffff0000, v108
	v_lshlrev_b32_e32 v190, 16, v104
	v_and_b32_e32 v191, 0xffff0000, v104
	v_pk_mul_f32 v[192:193], v[2:3], v[184:185]
	v_pk_fma_f32 v[192:193], v[10:11], v[186:187], v[192:193]
	v_pk_fma_f32 v[192:193], v[18:19], v[188:189], v[192:193]
	v_pk_mul_f32 v[168:169], v[192:193], v[190:191]
	v_pk_mul_f32 v[194:195], v[168:169], v[168:169]
	v_lshlrev_b32_e32 v184, 16, v117
	v_and_b32_e32 v185, 0xffff0000, v117
	v_lshlrev_b32_e32 v186, 16, v113
	v_and_b32_e32 v187, 0xffff0000, v113
	v_lshlrev_b32_e32 v188, 16, v109
	v_and_b32_e32 v189, 0xffff0000, v109
	v_lshlrev_b32_e32 v190, 16, v105
	v_and_b32_e32 v191, 0xffff0000, v105
	v_pk_mul_f32 v[192:193], v[4:5], v[184:185]
	v_pk_fma_f32 v[192:193], v[12:13], v[186:187], v[192:193]
	v_pk_fma_f32 v[192:193], v[20:21], v[188:189], v[192:193]
	v_pk_mul_f32 v[170:171], v[192:193], v[190:191]
	v_pk_fma_f32 v[194:195], v[170:171], v[170:171], v[194:195]
	v_lshlrev_b32_e32 v184, 16, v118
	v_and_b32_e32 v185, 0xffff0000, v118
	v_lshlrev_b32_e32 v186, 16, v114
	v_and_b32_e32 v187, 0xffff0000, v114
	v_lshlrev_b32_e32 v188, 16, v110
	v_and_b32_e32 v189, 0xffff0000, v110
	v_lshlrev_b32_e32 v190, 16, v106
	v_and_b32_e32 v191, 0xffff0000, v106
	v_pk_mul_f32 v[192:193], v[6:7], v[184:185]
	v_pk_fma_f32 v[192:193], v[14:15], v[186:187], v[192:193]
	v_pk_fma_f32 v[192:193], v[22:23], v[188:189], v[192:193]
	v_pk_mul_f32 v[172:173], v[192:193], v[190:191]
	v_pk_fma_f32 v[194:195], v[172:173], v[172:173], v[194:195]
	v_lshlrev_b32_e32 v184, 16, v119
	v_and_b32_e32 v185, 0xffff0000, v119
	v_lshlrev_b32_e32 v186, 16, v115
	v_and_b32_e32 v187, 0xffff0000, v115
	v_lshlrev_b32_e32 v188, 16, v111
	v_and_b32_e32 v189, 0xffff0000, v111
	v_lshlrev_b32_e32 v190, 16, v107
	v_and_b32_e32 v191, 0xffff0000, v107
	v_pk_mul_f32 v[192:193], v[8:9], v[184:185]
	v_pk_fma_f32 v[192:193], v[16:17], v[186:187], v[192:193]
	v_pk_fma_f32 v[192:193], v[24:25], v[188:189], v[192:193]
	v_pk_mul_f32 v[174:175], v[192:193], v[190:191]
	v_pk_fma_f32 v[194:195], v[174:175], v[174:175], v[194:195]
	v_add_f32_e32 v48, v194, v195
	s_waitcnt vmcnt(0)
	s_add_i32 s10, s24, 0x1e00
	s_and_b32 s11, s10, 0xfff
	s_cmp_lg_u32 s11, 0
	s_cbranch_scc1 .Lc5_k1_5
	v_mov_b32_e32 v128, 0
	v_mov_b32_e32 v129, 0
	v_mov_b32_e32 v130, 0
	v_mov_b32_e32 v131, 0

; __device__ __forceinline__ float wave_sum(float v) {
; #pragma unroll
;     for (int o = 1; o < 64; o <<= 1) v += __shfl_xor(v, o);
;     return v;
; }
; template <int NR>
; __device__ __forceinline__ void conv_rows(const Args& a, int r0, int rstride, int lane) {
;     ...
;     for (int i = 0; i < NR; ++i) { const int row = r0 + i * rstride; float y[8]; float s = 0.f;
; #pragma unroll
;         for (int j = 0; j < 8; ++j) { const int sh = (j & 1) * 16; const unsigned ub = bq[i][j >> 1], x0 = u0[i][j >> 1], x1 = u1[i][j >> 1], x2 = u2[i][j >> 1];
;             const float B = __uint_as_float(((ub >> sh) & 0xffffu) << 16), c_0 = __uint_as_float(((x0 >> sh) & 0xffffu) << 16), c_1 = __uint_as_float(((x1 >> sh) & 0xffffu) << 16), c_2 = __uint_as_float(((x2 >> sh) & 0xffffu) << 16);
;             const float k0 = j < 4 ? w0a[j & 3] : w0b[j & 3], k1 = j < 4 ? w1a[j & 3] : w1b[j & 3], k2 = j < 4 ? w2a[j & 3] : w2b[j & 3];
;             y[j] = B * (k0 * c_2 + k1 * c_1 + k2 * c_0); s += y[j] * y[j]; }
;         s = wave_sum(s); const float rs = rsqrtf(s * (1.f / 512.f) + EPS);
.Lc5_k2_5:
	v_lshlrev_b32_e32 v184, 16, v132
	v_and_b32_e32 v185, 0xffff0000, v132
	v_lshlrev_b32_e32 v186, 16, v128
	v_and_b32_e32 v187, 0xffff0000, v128
	v_lshlrev_b32_e32 v188, 16, v124
	v_and_b32_e32 v189, 0xffff0000, v124
	v_lshlrev_b32_e32 v190, 16, v120
	v_and_b32_e32 v191, 0xffff0000, v120
	v_pk_mul_f32 v[192:193], v[2:3], v[184:185]
	v_pk_fma_f32 v[192:193], v[10:11], v[186:187], v[192:193]
	v_pk_fma_f32 v[192:193], v[18:19], v[188:189], v[192:193]
	v_pk_mul_f32 v[176:177], v[192:193], v[190:191]
	v_pk_mul_f32 v[194:195], v[176:177], v[176:177]
	v_lshlrev_b32_e32 v184, 16, v133
	v_and_b32_e32 v185, 0xffff0000, v133
	v_lshlrev_b32_e32 v186, 16, v129
	v_and_b32_e32 v187, 0xffff0000, v129
	v_lshlrev_b32_e32 v188, 16, v125
	v_and_b32_e32 v189, 0xffff0000, v125
	v_lshlrev_b32_e32 v190, 16, v121
	v_and_b32_e32 v191, 0xffff0000, v121
	v_pk_mul_f32 v[192:193], v[4:5], v[184:185]
	v_pk_fma_f32 v[192:193], v[12:13], v[186:187], v[192:193]
	v_pk_fma_f32 v[192:193], v[20:21], v[188:189], v[192:193]
	v_pk_mul_f32 v[178:179], v[192:193], v[190:191]
	v_pk_fma_f32 v[194:195], v[178:179], v[178:179], v[194:195]
	v_lshlrev_b32_e32 v184, 16, v134
	v_and_b32_e32 v185, 0xffff0000, v134
	v_lshlrev_b32_e32 v186, 16, v130
	v_and_b32_e32 v187, 0xffff0000, v130
	v_lshlrev_b32_e32 v188, 16, v126
	v_and_b32_e32 v189, 0xffff0000, v126
	v_lshlrev_b32_e32 v190, 16, v122
	v_and_b32_e32 v191, 0xffff0000, v122
	v_pk_mul_f32 v[192:193], v[6:7], v[184:185]
	v_pk_fma_f32 v[192:193], v[14:15], v[186:187], v[192:193]
	v_pk_fma_f32 v[192:193], v[22:23], v[188:189], v[192:193]
	v_pk_mul_f32 v[180:181], v[192:193], v[190:191]
	v_pk_fma_f32 v[194:195], v[180:181], v[180:181], v[194:195]
	v_lshlrev_b32_e32 v184, 16, v135
	v_and_b32_e32 v185, 0xffff0000, v135
	v_lshlrev_b32_e32 v186, 16, v131
	v_and_b32_e32 v187, 0xffff0000, v131
	v_lshlrev_b32_e32 v188, 16, v127
	v_and_b32_e32 v189, 0xffff0000, v127
	v_lshlrev_b32_e32 v190, 16, v123
	v_and_b32_e32 v191, 0xffff0000, v123
	v_pk_mul_f32 v[192:193], v[8:9], v[184:185]
	v_pk_fma_f32 v[192:193], v[16:17], v[186:187], v[192:193]
	v_pk_fma_f32 v[192:193], v[24:25], v[188:189], v[192:193]
	v_pk_mul_f32 v[182:183], v[192:193], v[190:191]
	v_pk_fma_f32 v[194:195], v[182:183], v[182:183], v[194:195]
	v_add_f32_e32 v50, v194, v195
	v_xor_b32_e32 v56, 32, v208
	v_lshlrev_b32_e32 v56, 2, v56
	v_xor_b32_e32 v57, 16, v208
	v_lshlrev_b32_e32 v57, 2, v57
	v_xor_b32_e32 v58, 8, v208
	v_lshlrev_b32_e32 v58, 2, v58
	v_xor_b32_e32 v59, 4, v208
	v_lshlrev_b32_e32 v59, 2, v59
	v_xor_b32_e32 v60, 2, v208
	v_lshlrev_b32_e32 v60, 2, v60
	v_xor_b32_e32 v61, 1, v208
	v_lshlrev_b32_e32 v61, 2, v61
	v_mov_b32_e32 v62, 0x358637bd
	ds_bpermute_b32 v64, v56, v40
	ds_bpermute_b32 v66, v56, v42
	ds_bpermute_b32 v68, v56, v44
	ds_bpermute_b32 v70, v56, v46
	ds_bpermute_b32 v72, v56, v48
	ds_bpermute_b32 v74, v56, v50
	s_waitcnt lgkmcnt(0)
	v_add_f32_e32 v40, v40, v64
	v_add_f32_e32 v42, v42, v66
	v_add_f32_e32 v44, v44, v68
	v_add_f32_e32 v46, v46, v70
	v_add_f32_e32 v48, v48, v72
	v_add_f32_e32 v50, v50, v74
	ds_bpermute_b32 v64, v57, v40
	ds_bpermute_b32 v66, v57, v42
	ds_bpermute_b32 v68, v57, v44
	ds_bpermute_b32 v70, v57, v46
	ds_bpermute_b32 v72, v57, v48
	ds_bpermute_b32 v74, v57, v50
	s_waitcnt lgkmcnt(0)
	v_add_f32_e32 v40, v40, v64
	v_add_f32_e32 v42, v42, v66
	v_add_f32_e32 v44, v44, v68
	v_add_f32_e32 v46, v46, v70
	v_add_f32_e32 v48, v48, v72
	v_add_f32_e32 v50, v50, v74
	ds_bpermute_b32 v64, v58, v40
	ds_bpermute_b32 v66, v58, v42
	ds_bpermute_b32 v68, v58, v44
	ds_bpermute_b32 v70, v58, v46
	ds_bpermute_b32 v72, v58, v48
	ds_bpermute_b32 v74, v58, v50
	s_waitcnt lgkmcnt(0)
	v_add_f32_e32 v40, v40, v64
	v_add_f32_e32 v42, v42, v66
	v_add_f32_e32 v44, v44, v68
	v_add_f32_e32 v46, v46, v70
	v_add_f32_e32 v48, v48, v72
	v_add_f32_e32 v50, v50, v74
	ds_bpermute_b32 v64, v59, v40
	ds_bpermute_b32 v66, v59, v42
	ds_bpermute_b32 v68, v59, v44
	ds_bpermute_b32 v70, v59, v46
	ds_bpermute_b32 v72, v59, v48
	ds_bpermute_b32 v74, v59, v50
	s_waitcnt lgkmcnt(0)
	v_add_f32_e32 v40, v40, v64
	v_add_f32_e32 v42, v42, v66
	v_add_f32_e32 v44, v44, v68
	v_add_f32_e32 v46, v46, v70
	v_add_f32_e32 v48, v48, v72
	v_add_f32_e32 v50, v50, v74
	ds_bpermute_b32 v64, v60, v40
	ds_bpermute_b32 v66, v60, v42
	ds_bpermute_b32 v68, v60, v44
	ds_bpermute_b32 v70, v60, v46
	ds_bpermute_b32 v72, v60, v48
	ds_bpermute_b32 v74, v60, v50
	s_waitcnt lgkmcnt(0)
	v_add_f32_e32 v40, v40, v64
	v_add_f32_e32 v42, v42, v66
	v_add_f32_e32 v44, v44, v68
	v_add_f32_e32 v46, v46, v70
	v_add_f32_e32 v48, v48, v72
	v_add_f32_e32 v50, v50, v74
	ds_bpermute_b32 v64, v61, v40
	ds_bpermute_b32 v66, v61, v42
	ds_bpermute_b32 v68, v61, v44
	ds_bpermute_b32 v70, v61, v46
	ds_bpermute_b32 v72, v61, v48
	ds_bpermute_b32 v74, v61, v50
	s_waitcnt lgkmcnt(0)
; __device__ __forceinline__ unsigned pk2(float lo, float hi) { return pg8::cvt_pk_bf16(lo, hi); }
; template <int NR>
; __device__ __forceinline__ void conv_rows(const Args& a, int r0, int rstride, int lane) {
;     ...
;     for (int i = 0; i < NR; ++i) { const int row = r0 + i * rstride, t = row & (SEQ - 1);
;         bq[i] = *(const v4u*)(BCp + (size_t)row * 512 + c0); u0[i] = *(const v4u*)(CUp + (size_t)row * 512 + c0);
;         u1[i] = (v4u){0, 0, 0, 0}; u2[i] = (v4u){0, 0, 0, 0};
;         if (t >= 1) u1[i] = *(const v4u*)(CUp + (size_t)(row - 1) * 512 + c0);
;         if (t >= 2) u2[i] = *(const v4u*)(CUp + (size_t)(row - 2) * 512 + c0); }
;     ...
;         s = wave_sum(s); const float rs = rsqrtf(s * (1.f / 512.f) + EPS);
;         v4u o; o.x = pk2(y[0] * rs * ga[0], y[1] * rs * ga[1]); o.y = pk2(y[2] * rs * ga[2], y[3] * rs * ga[3]); o.z = pk2(y[4] * rs * gb[0], y[5] * rs * gb[1]); o.w = pk2(y[6] * rs * gb[2], y[7] * rs * gb[3]);
;         pg8::st_wt16((bf16*)(ws + WS_MIX) + (size_t)row * 1024 + 512 + c0, o); }
	v_add_f32_e32 v40, v40, v64
	v_add_f32_e32 v42, v42, v66
	v_add_f32_e32 v44, v44, v68
	v_add_f32_e32 v46, v46, v70
	v_add_f32_e32 v48, v48, v72
	v_add_f32_e32 v50, v50, v74
	v_fmamk_f32 v40, v40, 0x3b000000, v62
	v_fmamk_f32 v42, v42, 0x3b000000, v62
	v_fmamk_f32 v44, v44, 0x3b000000, v62
	v_fmamk_f32 v46, v46, 0x3b000000, v62
	v_fmamk_f32 v48, v48, 0x3b000000, v62
	v_fmamk_f32 v50, v50, 0x3b000000, v62
	v_rsq_f32_e32 v40, v40
	v_rsq_f32_e32 v42, v42
	v_rsq_f32_e32 v44, v44
	v_rsq_f32_e32 v46, v46
	v_rsq_f32_e32 v48, v48
	v_rsq_f32_e32 v50, v50
	s_nop 1
	v_pk_mul_f32 v[184:185], v[136:137], v[40:41] op_sel_hi:[1,0]
	v_pk_mul_f32 v[186:187], v[138:139], v[40:41] op_sel_hi:[1,0]
	v_pk_mul_f32 v[188:189], v[140:141], v[40:41] op_sel_hi:[1,0]
	v_pk_mul_f32 v[190:191], v[142:143], v[40:41] op_sel_hi:[1,0]
	v_pk_mul_f32 v[184:185], v[26:27], v[184:185]
	v_pk_mul_f32 v[186:187], v[28:29], v[186:187]
	v_pk_mul_f32 v[188:189], v[30:31], v[188:189]
	v_pk_mul_f32 v[190:191], v[32:33], v[190:191]
	v_cvt_pk_bf16_f32 v88, v184, v185
	v_cvt_pk_bf16_f32 v89, v186, v187
	v_cvt_pk_bf16_f32 v90, v188, v189
	v_cvt_pk_bf16_f32 v91, v190, v191
	s_add_i32 s10, s24, 0x0
	s_lshl_b32 s11, s10, 11
	s_add_u32 s4, s26, s11
	s_addc_u32 s5, s27, 0
	global_store_dwordx4 v0, v[88:91], s[4:5] offset:1024
	v_pk_mul_f32 v[184:185], v[144:145], v[42:43] op_sel_hi:[1,0]
	v_pk_mul_f32 v[186:187], v[146:147], v[42:43] op_sel_hi:[1,0]
	v_pk_mul_f32 v[188:189], v[148:149], v[42:43] op_sel_hi:[1,0]
	v_pk_mul_f32 v[190:191], v[150:151], v[42:43] op_sel_hi:[1,0]
	v_pk_mul_f32 v[184:185], v[26:27], v[184:185]
	v_pk_mul_f32 v[186:187], v[28:29], v[186:187]
	v_pk_mul_f32 v[188:189], v[30:31], v[188:189]
	v_pk_mul_f32 v[190:191], v[32:33], v[190:191]
	v_cvt_pk_bf16_f32 v92, v184, v185
	v_cvt_pk_bf16_f32 v93, v186, v187
	v_cvt_pk_bf16_f32 v94, v188, v189
	v_cvt_pk_bf16_f32 v95, v190, v191
	s_add_i32 s10, s24, 0x600
	s_lshl_b32 s11, s10, 11
	s_add_u32 s4, s26, s11
	s_addc_u32 s5, s27, 0
	global_store_dwordx4 v0, v[92:95], s[4:5] offset:1024
	v_pk_mul_f32 v[184:185], v[152:153], v[44:45] op_sel_hi:[1,0]
	v_pk_mul_f32 v[186:187], v[154:155], v[44:45] op_sel_hi:[1,0]
	v_pk_mul_f32 v[188:189], v[156:157], v[44:45] op_sel_hi:[1,0]
	v_pk_mul_f32 v[190:191], v[158:159], v[44:45] op_sel_hi:[1,0]
	v_pk_mul_f32 v[184:185], v[26:27], v[184:185]
	v_pk_mul_f32 v[186:187], v[28:29], v[186:187]
	v_pk_mul_f32 v[188:189], v[30:31], v[188:189]
	v_pk_mul_f32 v[190:191], v[32:33], v[190:191]
	v_cvt_pk_bf16_f32 v96, v184, v185
	v_cvt_pk_bf16_f32 v97, v186, v187
	v_cvt_pk_bf16_f32 v98, v188, v189
	v_cvt_pk_bf16_f32 v99, v190, v191
	s_add_i32 s10, s24, 0xc00
	s_lshl_b32 s11, s10, 11
	s_add_u32 s4, s26, s11
	s_addc_u32 s5, s27, 0
	global_store_dwordx4 v0, v[96:99], s[4:5] offset:1024
	v_pk_mul_f32 v[184:185], v[160:161], v[46:47] op_sel_hi:[1,0]
	v_pk_mul_f32 v[186:187], v[162:163], v[46:47] op_sel_hi:[1,0]
	v_pk_mul_f32 v[188:189], v[164:165], v[46:47] op_sel_hi:[1,0]
	v_pk_mul_f32 v[190:191], v[166:167], v[46:47] op_sel_hi:[1,0]
	v_pk_mul_f32 v[184:185], v[26:27], v[184:185]
	v_pk_mul_f32 v[186:187], v[28:29], v[186:187]
	v_pk_mul_f32 v[188:189], v[30:31], v[188:189]
	v_pk_mul_f32 v[190:191], v[32:33], v[190:191]
	v_cvt_pk_bf16_f32 v100, v184, v185
	v_cvt_pk_bf16_f32 v101, v186, v187
	v_cvt_pk_bf16_f32 v102, v188, v189
	v_cvt_pk_bf16_f32 v103, v190, v191
	s_add_i32 s10, s24, 0x1200
	s_lshl_b32 s11, s10, 11
	s_add_u32 s4, s26, s11
	s_addc_u32 s5, s27, 0
	global_store_dwordx4 v0, v[100:103], s[4:5] offset:1024
	v_pk_mul_f32 v[184:185], v[168:169], v[48:49] op_sel_hi:[1,0]
	v_pk_mul_f32 v[186:187], v[170:171], v[48:49] op_sel_hi:[1,0]
	v_pk_mul_f32 v[188:189], v[172:173], v[48:49] op_sel_hi:[1,0]
	v_pk_mul_f32 v[190:191], v[174:175], v[48:49] op_sel_hi:[1,0]
	v_pk_mul_f32 v[184:185], v[26:27], v[184:185]
	v_pk_mul_f32 v[186:187], v[28:29], v[186:187]
	v_pk_mul_f32 v[188:189], v[30:31], v[188:189]
	v_pk_mul_f32 v[190:191], v[32:33], v[190:191]
	v_cvt_pk_bf16_f32 v104, v184, v185
	v_cvt_pk_bf16_f32 v105, v186, v187
	v_cvt_pk_bf16_f32 v106, v188, v189
	v_cvt_pk_bf16_f32 v107, v190, v191
	s_add_i32 s10, s24, 0x1800
	s_lshl_b32 s11, s10, 11
	s_add_u32 s4, s26, s11
	s_addc_u32 s5, s27, 0
	global_store_dwordx4 v0, v[104:107], s[4:5] offset:1024
	v_pk_mul_f32 v[184:185], v[176:177], v[50:51] op_sel_hi:[1,0]
	v_pk_mul_f32 v[186:187], v[178:179], v[50:51] op_sel_hi:[1,0]
	v_pk_mul_f32 v[188:189], v[180:181], v[50:51] op_sel_hi:[1,0]
	v_pk_mul_f32 v[190:191], v[182:183], v[50:51] op_sel_hi:[1,0]
	v_pk_mul_f32 v[184:185], v[26:27], v[184:185]
	v_pk_mul_f32 v[186:187], v[28:29], v[186:187]
	v_pk_mul_f32 v[188:189], v[30:31], v[188:189]
	v_pk_mul_f32 v[190:191], v[32:33], v[190:191]
	v_cvt_pk_bf16_f32 v108, v184, v185
	v_cvt_pk_bf16_f32 v109, v186, v187
	v_cvt_pk_bf16_f32 v110, v188, v189
	v_cvt_pk_bf16_f32 v111, v190, v191
	s_add_i32 s10, s24, 0x1e00
	s_lshl_b32 s11, s10, 11
	s_add_u32 s4, s26, s11
	s_addc_u32 s5, s27, 0
	global_store_dwordx4 v0, v[108:111], s[4:5] offset:1024
	s_add_i32 s10, s24, 0x2400
	s_lshl_b32 s11, s10, 10
	s_add_u32 s4, s20, s11
	s_addc_u32 s5, s21, 0
	s_add_u32 s6, s22, s11
	s_addc_u32 s7, s23, 0
	global_load_dwordx4 v[40:43], v0, s[4:5]
	global_load_dwordx4 v[44:47], v0, s[6:7]
	global_load_dwordx4 v[48:51], v0, s[6:7] offset:-1024
	global_load_dwordx4 v[52:55], v0, s[6:7] offset:-2048
	s_add_i32 s10, s24, 0x2a00
	s_lshl_b32 s11, s10, 10
	s_add_u32 s4, s20, s11
	s_addc_u32 s5, s21, 0
	s_add_u32 s6, s22, s11
	s_addc_u32 s7, s23, 0
	global_load_dwordx4 v[56:59], v0, s[4:5]
	global_load_dwordx4 v[60:63], v0, s[6:7]
	global_load_dwordx4 v[64:67], v0, s[6:7] offset:-1024
	global_load_dwordx4 v[68:71], v0, s[6:7] offset:-2048
	s_add_i32 s10, s24, 0x3000
	s_lshl_b32 s11, s10, 10
	s_add_u32 s4, s20, s11
	s_addc_u32 s5, s21, 0
	s_add_u32 s6, s22, s11
	s_addc_u32 s7, s23, 0
	global_load_dwordx4 v[72:75], v0, s[4:5]
	global_load_dwordx4 v[76:79], v0, s[6:7]
	global_load_dwordx4 v[80:83], v0, s[6:7] offset:-1024
	global_load_dwordx4 v[84:87], v0, s[6:7] offset:-2048
	s_add_i32 s10, s24, 0x3600
	s_lshl_b32 s11, s10, 10
	s_add_u32 s4, s20, s11
	s_addc_u32 s5, s21, 0
	s_add_u32 s6, s22, s11
	s_addc_u32 s7, s23, 0
	global_load_dwordx4 v[88:91], v0, s[4:5]
	global_load_dwordx4 v[92:95], v0, s[6:7]
	global_load_dwordx4 v[96:99], v0, s[6:7] offset:-1024
	global_load_dwordx4 v[100:103], v0, s[6:7] offset:-2048
	s_add_i32 s10, s24, 0x3c00
	s_cmpk_lt_u32 s24, 0x400
	s_cselect_b32 s10, s10, s24
	s_lshl_b32 s11, s10, 10
	s_add_u32 s4, s20, s11
	s_addc_u32 s5, s21, 0
	s_add_u32 s6, s22, s11
	s_addc_u32 s7, s23, 0
	global_load_dwordx4 v[104:107], v0, s[4:5]
	global_load_dwordx4 v[108:111], v0, s[6:7]
	global_load_dwordx4 v[112:115], v0, s[6:7] offset:-1024
	global_load_dwordx4 v[116:119], v0, s[6:7] offset:-2048
	s_waitcnt vmcnt(16)
	s_add_i32 s10, s24, 0x2400
	s_and_b32 s11, s10, 0xfff
	s_cmp_lg_u32 s11, 0
	s_cbranch_scc1 .Lc5_k1_6
	v_mov_b32_e32 v48, 0
	v_mov_b32_e32 v49, 0
	v_mov_b32_e32 v50, 0
	v_mov_b32_e32 v51, 0

; template <int NR>
; __device__ __forceinline__ void conv_rows(const Args& a, int r0, int rstride, int lane) {
;     ...
;     for (int i = 0; i < NR; ++i) { const int row = r0 + i * rstride; float y[8]; float s = 0.f;
; #pragma unroll
;         for (int j = 0; j < 8; ++j) { const int sh = (j & 1) * 16; const unsigned ub = bq[i][j >> 1], x0 = u0[i][j >> 1], x1 = u1[i][j >> 1], x2 = u2[i][j >> 1];
;             const float B = __uint_as_float(((ub >> sh) & 0xffffu) << 16), c_0 = __uint_as_float(((x0 >> sh) & 0xffffu) << 16), c_1 = __uint_as_float(((x1 >> sh) & 0xffffu) << 16), c_2 = __uint_as_float(((x2 >> sh) & 0xffffu) << 16);
;             const float k0 = j < 4 ? w0a[j & 3] : w0b[j & 3], k1 = j < 4 ? w1a[j & 3] : w1b[j & 3], k2 = j < 4 ? w2a[j & 3] : w2b[j & 3];
;             y[j] = B * (k0 * c_2 + k1 * c_1 + k2 * c_0); s += y[j] * y[j]; }
.Lc5_k2_6:
	v_lshlrev_b32_e32 v184, 16, v52
	v_and_b32_e32 v185, 0xffff0000, v52
	v_lshlrev_b32_e32 v186, 16, v48
	v_and_b32_e32 v187, 0xffff0000, v48
	v_lshlrev_b32_e32 v188, 16, v44
	v_and_b32_e32 v189, 0xffff0000, v44
	v_lshlrev_b32_e32 v190, 16, v40
	v_and_b32_e32 v191, 0xffff0000, v40
	v_pk_mul_f32 v[192:193], v[2:3], v[184:185]
	v_pk_fma_f32 v[192:193], v[10:11], v[186:187], v[192:193]
	v_pk_fma_f32 v[192:193], v[18:19], v[188:189], v[192:193]
	v_pk_mul_f32 v[136:137], v[192:193], v[190:191]
	v_pk_mul_f32 v[194:195], v[136:137], v[136:137]
	v_lshlrev_b32_e32 v184, 16, v53
	v_and_b32_e32 v185, 0xffff0000, v53
	v_lshlrev_b32_e32 v186, 16, v49
	v_and_b32_e32 v187, 0xffff0000, v49
	v_lshlrev_b32_e32 v188, 16, v45
	v_and_b32_e32 v189, 0xffff0000, v45
	v_lshlrev_b32_e32 v190, 16, v41
	v_and_b32_e32 v191, 0xffff0000, v41
	v_pk_mul_f32 v[192:193], v[4:5], v[184:185]
	v_pk_fma_f32 v[192:193], v[12:13], v[186:187], v[192:193]
	v_pk_fma_f32 v[192:193], v[20:21], v[188:189], v[192:193]
	v_pk_mul_f32 v[138:139], v[192:193], v[190:191]
	v_pk_fma_f32 v[194:195], v[138:139], v[138:139], v[194:195]
	v_lshlrev_b32_e32 v184, 16, v54
	v_and_b32_e32 v185, 0xffff0000, v54
	v_lshlrev_b32_e32 v186, 16, v50
	v_and_b32_e32 v187, 0xffff0000, v50
	v_lshlrev_b32_e32 v188, 16, v46
	v_and_b32_e32 v189, 0xffff0000, v46
	v_lshlrev_b32_e32 v190, 16, v42
	v_and_b32_e32 v191, 0xffff0000, v42
	v_pk_mul_f32 v[192:193], v[6:7], v[184:185]
	v_pk_fma_f32 v[192:193], v[14:15], v[186:187], v[192:193]
	v_pk_fma_f32 v[192:193], v[22:23], v[188:189], v[192:193]
	v_pk_mul_f32 v[140:141], v[192:193], v[190:191]
	v_pk_fma_f32 v[194:195], v[140:141], v[140:141], v[194:195]
	v_lshlrev_b32_e32 v184, 16, v55
	v_and_b32_e32 v185, 0xffff0000, v55
	v_lshlrev_b32_e32 v186, 16, v51
	v_and_b32_e32 v187, 0xffff0000, v51
	v_lshlrev_b32_e32 v188, 16, v47
	v_and_b32_e32 v189, 0xffff0000, v47
	v_lshlrev_b32_e32 v190, 16, v43
	v_and_b32_e32 v191, 0xffff0000, v43
	v_pk_mul_f32 v[192:193], v[8:9], v[184:185]
	v_pk_fma_f32 v[192:193], v[16:17], v[186:187], v[192:193]
	v_pk_fma_f32 v[192:193], v[24:25], v[188:189], v[192:193]
	v_pk_mul_f32 v[142:143], v[192:193], v[190:191]
	v_pk_fma_f32 v[194:195], v[142:143], v[142:143], v[194:195]
	v_add_f32_e32 v40, v194, v195
	s_waitcnt vmcnt(12)
	s_add_i32 s10, s24, 0x2a00
	s_and_b32 s11, s10, 0xfff
	s_cmp_lg_u32 s11, 0
	s_cbranch_scc1 .Lc5_k1_7
	v_mov_b32_e32 v64, 0
	v_mov_b32_e32 v65, 0
	v_mov_b32_e32 v66, 0
	v_mov_b32_e32 v67, 0

; template <int NR>
; __device__ __forceinline__ void conv_rows(const Args& a, int r0, int rstride, int lane) {
;     ...
;     for (int i = 0; i < NR; ++i) { const int row = r0 + i * rstride; float y[8]; float s = 0.f;
; #pragma unroll
;         for (int j = 0; j < 8; ++j) { const int sh = (j & 1) * 16; const unsigned ub = bq[i][j >> 1], x0 = u0[i][j >> 1], x1 = u1[i][j >> 1], x2 = u2[i][j >> 1];
;             const float B = __uint_as_float(((ub >> sh) & 0xffffu) << 16), c_0 = __uint_as_float(((x0 >> sh) & 0xffffu) << 16), c_1 = __uint_as_float(((x1 >> sh) & 0xffffu) << 16), c_2 = __uint_as_float(((x2 >> sh) & 0xffffu) << 16);
;             const float k0 = j < 4 ? w0a[j & 3] : w0b[j & 3], k1 = j < 4 ? w1a[j & 3] : w1b[j & 3], k2 = j < 4 ? w2a[j & 3] : w2b[j & 3];
;             y[j] = B * (k0 * c_2 + k1 * c_1 + k2 * c_0); s += y[j] * y[j]; }
.Lc5_k2_7:
	v_lshlrev_b32_e32 v184, 16, v68
	v_and_b32_e32 v185, 0xffff0000, v68
	v_lshlrev_b32_e32 v186, 16, v64
	v_and_b32_e32 v187, 0xffff0000, v64
	v_lshlrev_b32_e32 v188, 16, v60
	v_and_b32_e32 v189, 0xffff0000, v60
	v_lshlrev_b32_e32 v190, 16, v56
	v_and_b32_e32 v191, 0xffff0000, v56
	v_pk_mul_f32 v[192:193], v[2:3], v[184:185]
	v_pk_fma_f32 v[192:193], v[10:11], v[186:187], v[192:193]
	v_pk_fma_f32 v[192:193], v[18:19], v[188:189], v[192:193]
	v_pk_mul_f32 v[144:145], v[192:193], v[190:191]
	v_pk_mul_f32 v[194:195], v[144:145], v[144:145]
	v_lshlrev_b32_e32 v184, 16, v69
	v_and_b32_e32 v185, 0xffff0000, v69
	v_lshlrev_b32_e32 v186, 16, v65
	v_and_b32_e32 v187, 0xffff0000, v65
	v_lshlrev_b32_e32 v188, 16, v61
	v_and_b32_e32 v189, 0xffff0000, v61
	v_lshlrev_b32_e32 v190, 16, v57
	v_and_b32_e32 v191, 0xffff0000, v57
	v_pk_mul_f32 v[192:193], v[4:5], v[184:185]
	v_pk_fma_f32 v[192:193], v[12:13], v[186:187], v[192:193]
	v_pk_fma_f32 v[192:193], v[20:21], v[188:189], v[192:193]
	v_pk_mul_f32 v[146:147], v[192:193], v[190:191]
	v_pk_fma_f32 v[194:195], v[146:147], v[146:147], v[194:195]
	v_lshlrev_b32_e32 v184, 16, v70
	v_and_b32_e32 v185, 0xffff0000, v70
	v_lshlrev_b32_e32 v186, 16, v66
	v_and_b32_e32 v187, 0xffff0000, v66
	v_lshlrev_b32_e32 v188, 16, v62
	v_and_b32_e32 v189, 0xffff0000, v62
	v_lshlrev_b32_e32 v190, 16, v58
	v_and_b32_e32 v191, 0xffff0000, v58
	v_pk_mul_f32 v[192:193], v[6:7], v[184:185]
	v_pk_fma_f32 v[192:193], v[14:15], v[186:187], v[192:193]
	v_pk_fma_f32 v[192:193], v[22:23], v[188:189], v[192:193]
	v_pk_mul_f32 v[148:149], v[192:193], v[190:191]
	v_pk_fma_f32 v[194:195], v[148:149], v[148:149], v[194:195]
	v_lshlrev_b32_e32 v184, 16, v71
	v_and_b32_e32 v185, 0xffff0000, v71
	v_lshlrev_b32_e32 v186, 16, v67
	v_and_b32_e32 v187, 0xffff0000, v67
	v_lshlrev_b32_e32 v188, 16, v63
	v_and_b32_e32 v189, 0xffff0000, v63
	v_lshlrev_b32_e32 v190, 16, v59
	v_and_b32_e32 v191, 0xffff0000, v59
	v_pk_mul_f32 v[192:193], v[8:9], v[184:185]
	v_pk_fma_f32 v[192:193], v[16:17], v[186:187], v[192:193]
	v_pk_fma_f32 v[192:193], v[24:25], v[188:189], v[192:193]
	v_pk_mul_f32 v[150:151], v[192:193], v[190:191]
	v_pk_fma_f32 v[194:195], v[150:151], v[150:151], v[194:195]
	v_add_f32_e32 v42, v194, v195
	s_waitcnt vmcnt(8)
	s_add_i32 s10, s24, 0x3000
	s_and_b32 s11, s10, 0xfff
	s_cmp_lg_u32 s11, 0
	s_cbranch_scc1 .Lc5_k1_8
	v_mov_b32_e32 v80, 0
	v_mov_b32_e32 v81, 0
	v_mov_b32_e32 v82, 0
	v_mov_b32_e32 v83, 0

; template <int NR>
; __device__ __forceinline__ void conv_rows(const Args& a, int r0, int rstride, int lane) {
;     ...
;     for (int i = 0; i < NR; ++i) { const int row = r0 + i * rstride; float y[8]; float s = 0.f;
; #pragma unroll
;         for (int j = 0; j < 8; ++j) { const int sh = (j & 1) * 16; const unsigned ub = bq[i][j >> 1], x0 = u0[i][j >> 1], x1 = u1[i][j >> 1], x2 = u2[i][j >> 1];
;             const float B = __uint_as_float(((ub >> sh) & 0xffffu) << 16), c_0 = __uint_as_float(((x0 >> sh) & 0xffffu) << 16), c_1 = __uint_as_float(((x1 >> sh) & 0xffffu) << 16), c_2 = __uint_as_float(((x2 >> sh) & 0xffffu) << 16);
;             const float k0 = j < 4 ? w0a[j & 3] : w0b[j & 3], k1 = j < 4 ? w1a[j & 3] : w1b[j & 3], k2 = j < 4 ? w2a[j & 3] : w2b[j & 3];
;             y[j] = B * (k0 * c_2 + k1 * c_1 + k2 * c_0); s += y[j] * y[j]; }
.Lc5_k2_8:
	v_lshlrev_b32_e32 v184, 16, v84
	v_and_b32_e32 v185, 0xffff0000, v84
	v_lshlrev_b32_e32 v186, 16, v80
	v_and_b32_e32 v187, 0xffff0000, v80
	v_lshlrev_b32_e32 v188, 16, v76
	v_and_b32_e32 v189, 0xffff0000, v76
	v_lshlrev_b32_e32 v190, 16, v72
	v_and_b32_e32 v191, 0xffff0000, v72
	v_pk_mul_f32 v[192:193], v[2:3], v[184:185]
	v_pk_fma_f32 v[192:193], v[10:11], v[186:187], v[192:193]
	v_pk_fma_f32 v[192:193], v[18:19], v[188:189], v[192:193]
	v_pk_mul_f32 v[152:153], v[192:193], v[190:191]
	v_pk_mul_f32 v[194:195], v[152:153], v[152:153]
	v_lshlrev_b32_e32 v184, 16, v85
	v_and_b32_e32 v185, 0xffff0000, v85
	v_lshlrev_b32_e32 v186, 16, v81
	v_and_b32_e32 v187, 0xffff0000, v81
	v_lshlrev_b32_e32 v188, 16, v77
	v_and_b32_e32 v189, 0xffff0000, v77
	v_lshlrev_b32_e32 v190, 16, v73
	v_and_b32_e32 v191, 0xffff0000, v73
	v_pk_mul_f32 v[192:193], v[4:5], v[184:185]
	v_pk_fma_f32 v[192:193], v[12:13], v[186:187], v[192:193]
	v_pk_fma_f32 v[192:193], v[20:21], v[188:189], v[192:193]
	v_pk_mul_f32 v[154:155], v[192:193], v[190:191]
	v_pk_fma_f32 v[194:195], v[154:155], v[154:155], v[194:195]
	v_lshlrev_b32_e32 v184, 16, v86
	v_and_b32_e32 v185, 0xffff0000, v86
	v_lshlrev_b32_e32 v186, 16, v82
	v_and_b32_e32 v187, 0xffff0000, v82
	v_lshlrev_b32_e32 v188, 16, v78
	v_and_b32_e32 v189, 0xffff0000, v78
	v_lshlrev_b32_e32 v190, 16, v74
	v_and_b32_e32 v191, 0xffff0000, v74
	v_pk_mul_f32 v[192:193], v[6:7], v[184:185]
	v_pk_fma_f32 v[192:193], v[14:15], v[186:187], v[192:193]
	v_pk_fma_f32 v[192:193], v[22:23], v[188:189], v[192:193]
	v_pk_mul_f32 v[156:157], v[192:193], v[190:191]
	v_pk_fma_f32 v[194:195], v[156:157], v[156:157], v[194:195]
	v_lshlrev_b32_e32 v184, 16, v87
	v_and_b32_e32 v185, 0xffff0000, v87
	v_lshlrev_b32_e32 v186, 16, v83
	v_and_b32_e32 v187, 0xffff0000, v83
	v_lshlrev_b32_e32 v188, 16, v79
	v_and_b32_e32 v189, 0xffff0000, v79
	v_lshlrev_b32_e32 v190, 16, v75
	v_and_b32_e32 v191, 0xffff0000, v75
	v_pk_mul_f32 v[192:193], v[8:9], v[184:185]
	v_pk_fma_f32 v[192:193], v[16:17], v[186:187], v[192:193]
	v_pk_fma_f32 v[192:193], v[24:25], v[188:189], v[192:193]
	v_pk_mul_f32 v[158:159], v[192:193], v[190:191]
	v_pk_fma_f32 v[194:195], v[158:159], v[158:159], v[194:195]
	v_add_f32_e32 v44, v194, v195
	s_waitcnt vmcnt(4)
	s_add_i32 s10, s24, 0x3600
	s_and_b32 s11, s10, 0xfff
	s_cmp_lg_u32 s11, 0
	s_cbranch_scc1 .Lc5_k1_9
	v_mov_b32_e32 v96, 0
	v_mov_b32_e32 v97, 0
	v_mov_b32_e32 v98, 0
	v_mov_b32_e32 v99, 0

; template <int NR>
; __device__ __forceinline__ void conv_rows(const Args& a, int r0, int rstride, int lane) {
;     ...
;     for (int i = 0; i < NR; ++i) { const int row = r0 + i * rstride; float y[8]; float s = 0.f;
; #pragma unroll
;         for (int j = 0; j < 8; ++j) { const int sh = (j & 1) * 16; const unsigned ub = bq[i][j >> 1], x0 = u0[i][j >> 1], x1 = u1[i][j >> 1], x2 = u2[i][j >> 1];
;             const float B = __uint_as_float(((ub >> sh) & 0xffffu) << 16), c_0 = __uint_as_float(((x0 >> sh) & 0xffffu) << 16), c_1 = __uint_as_float(((x1 >> sh) & 0xffffu) << 16), c_2 = __uint_as_float(((x2 >> sh) & 0xffffu) << 16);
;             const float k0 = j < 4 ? w0a[j & 3] : w0b[j & 3], k1 = j < 4 ? w1a[j & 3] : w1b[j & 3], k2 = j < 4 ? w2a[j & 3] : w2b[j & 3];
;             y[j] = B * (k0 * c_2 + k1 * c_1 + k2 * c_0); s += y[j] * y[j]; }
.Lc5_k2_9:
	v_lshlrev_b32_e32 v184, 16, v100
	v_and_b32_e32 v185, 0xffff0000, v100
	v_lshlrev_b32_e32 v186, 16, v96
	v_and_b32_e32 v187, 0xffff0000, v96
	v_lshlrev_b32_e32 v188, 16, v92
	v_and_b32_e32 v189, 0xffff0000, v92
	v_lshlrev_b32_e32 v190, 16, v88
	v_and_b32_e32 v191, 0xffff0000, v88
	v_pk_mul_f32 v[192:193], v[2:3], v[184:185]
	v_pk_fma_f32 v[192:193], v[10:11], v[186:187], v[192:193]
	v_pk_fma_f32 v[192:193], v[18:19], v[188:189], v[192:193]
	v_pk_mul_f32 v[160:161], v[192:193], v[190:191]
	v_pk_mul_f32 v[194:195], v[160:161], v[160:161]
	v_lshlrev_b32_e32 v184, 16, v101
	v_and_b32_e32 v185, 0xffff0000, v101
	v_lshlrev_b32_e32 v186, 16, v97
	v_and_b32_e32 v187, 0xffff0000, v97
	v_lshlrev_b32_e32 v188, 16, v93
	v_and_b32_e32 v189, 0xffff0000, v93
	v_lshlrev_b32_e32 v190, 16, v89
	v_and_b32_e32 v191, 0xffff0000, v89
	v_pk_mul_f32 v[192:193], v[4:5], v[184:185]
	v_pk_fma_f32 v[192:193], v[12:13], v[186:187], v[192:193]
	v_pk_fma_f32 v[192:193], v[20:21], v[188:189], v[192:193]
	v_pk_mul_f32 v[162:163], v[192:193], v[190:191]
	v_pk_fma_f32 v[194:195], v[162:163], v[162:163], v[194:195]
	v_lshlrev_b32_e32 v184, 16, v102
	v_and_b32_e32 v185, 0xffff0000, v102
	v_lshlrev_b32_e32 v186, 16, v98
	v_and_b32_e32 v187, 0xffff0000, v98
	v_lshlrev_b32_e32 v188, 16, v94
	v_and_b32_e32 v189, 0xffff0000, v94
	v_lshlrev_b32_e32 v190, 16, v90
	v_and_b32_e32 v191, 0xffff0000, v90
	v_pk_mul_f32 v[192:193], v[6:7], v[184:185]
	v_pk_fma_f32 v[192:193], v[14:15], v[186:187], v[192:193]
	v_pk_fma_f32 v[192:193], v[22:23], v[188:189], v[192:193]
	v_pk_mul_f32 v[164:165], v[192:193], v[190:191]
	v_pk_fma_f32 v[194:195], v[164:165], v[164:165], v[194:195]
	v_lshlrev_b32_e32 v184, 16, v103
	v_and_b32_e32 v185, 0xffff0000, v103
	v_lshlrev_b32_e32 v186, 16, v99
	v_and_b32_e32 v187, 0xffff0000, v99
	v_lshlrev_b32_e32 v188, 16, v95
	v_and_b32_e32 v189, 0xffff0000, v95
	v_lshlrev_b32_e32 v190, 16, v91
	v_and_b32_e32 v191, 0xffff0000, v91
	v_pk_mul_f32 v[192:193], v[8:9], v[184:185]
	v_pk_fma_f32 v[192:193], v[16:17], v[186:187], v[192:193]
	v_pk_fma_f32 v[192:193], v[24:25], v[188:189], v[192:193]
	v_pk_mul_f32 v[166:167], v[192:193], v[190:191]
	v_pk_fma_f32 v[194:195], v[166:167], v[166:167], v[194:195]
	v_add_f32_e32 v46, v194, v195
	s_waitcnt vmcnt(0)
	s_add_i32 s10, s24, 0x3c00
	s_cmpk_lt_u32 s24, 0x400
	s_cselect_b32 s10, s10, s24
	s_and_b32 s11, s10, 0xfff
	s_cmp_lg_u32 s11, 0
	s_cbranch_scc1 .Lc5_k1_10
	v_mov_b32_e32 v112, 0
	v_mov_b32_e32 v113, 0
	v_mov_b32_e32 v114, 0
	v_mov_b32_e32 v115, 0

; __device__ __forceinline__ float wave_sum(float v) {
; #pragma unroll
;     for (int o = 1; o < 64; o <<= 1) v += __shfl_xor(v, o);
;     return v;
; }
; template <int NR>
; __device__ __forceinline__ void conv_rows(const Args& a, int r0, int rstride, int lane) {
;     ...
;     for (int i = 0; i < NR; ++i) { const int row = r0 + i * rstride; float y[8]; float s = 0.f;
; #pragma unroll
;         for (int j = 0; j < 8; ++j) { const int sh = (j & 1) * 16; const unsigned ub = bq[i][j >> 1], x0 = u0[i][j >> 1], x1 = u1[i][j >> 1], x2 = u2[i][j >> 1];
;             const float B = __uint_as_float(((ub >> sh) & 0xffffu) << 16), c_0 = __uint_as_float(((x0 >> sh) & 0xffffu) << 16), c_1 = __uint_as_float(((x1 >> sh) & 0xffffu) << 16), c_2 = __uint_as_float(((x2 >> sh) & 0xffffu) << 16);
;             const float k0 = j < 4 ? w0a[j & 3] : w0b[j & 3], k1 = j < 4 ? w1a[j & 3] : w1b[j & 3], k2 = j < 4 ? w2a[j & 3] : w2b[j & 3];
;             y[j] = B * (k0 * c_2 + k1 * c_1 + k2 * c_0); s += y[j] * y[j]; }
;         s = wave_sum(s); const float rs = rsqrtf(s * (1.f / 512.f) + EPS);
.Lc5_k2_10:
	v_lshlrev_b32_e32 v184, 16, v116
	v_and_b32_e32 v185, 0xffff0000, v116
	v_lshlrev_b32_e32 v186, 16, v112
	v_and_b32_e32 v187, 0xffff0000, v112
	v_lshlrev_b32_e32 v188, 16, v108
	v_and_b32_e32 v189, 0xffff0000, v108
	v_lshlrev_b32_e32 v190, 16, v104
	v_and_b32_e32 v191, 0xffff0000, v104
	v_pk_mul_f32 v[192:193], v[2:3], v[184:185]
	v_pk_fma_f32 v[192:193], v[10:11], v[186:187], v[192:193]
	v_pk_fma_f32 v[192:193], v[18:19], v[188:189], v[192:193]
	v_pk_mul_f32 v[168:169], v[192:193], v[190:191]
	v_pk_mul_f32 v[194:195], v[168:169], v[168:169]
	v_lshlrev_b32_e32 v184, 16, v117
	v_and_b32_e32 v185, 0xffff0000, v117
	v_lshlrev_b32_e32 v186, 16, v113
	v_and_b32_e32 v187, 0xffff0000, v113
	v_lshlrev_b32_e32 v188, 16, v109
	v_and_b32_e32 v189, 0xffff0000, v109
	v_lshlrev_b32_e32 v190, 16, v105
	v_and_b32_e32 v191, 0xffff0000, v105
	v_pk_mul_f32 v[192:193], v[4:5], v[184:185]
	v_pk_fma_f32 v[192:193], v[12:13], v[186:187], v[192:193]
	v_pk_fma_f32 v[192:193], v[20:21], v[188:189], v[192:193]
	v_pk_mul_f32 v[170:171], v[192:193], v[190:191]
	v_pk_fma_f32 v[194:195], v[170:171], v[170:171], v[194:195]
	v_lshlrev_b32_e32 v184, 16, v118
	v_and_b32_e32 v185, 0xffff0000, v118
	v_lshlrev_b32_e32 v186, 16, v114
	v_and_b32_e32 v187, 0xffff0000, v114
	v_lshlrev_b32_e32 v188, 16, v110
	v_and_b32_e32 v189, 0xffff0000, v110
	v_lshlrev_b32_e32 v190, 16, v106
	v_and_b32_e32 v191, 0xffff0000, v106
	v_pk_mul_f32 v[192:193], v[6:7], v[184:185]
	v_pk_fma_f32 v[192:193], v[14:15], v[186:187], v[192:193]
	v_pk_fma_f32 v[192:193], v[22:23], v[188:189], v[192:193]
	v_pk_mul_f32 v[172:173], v[192:193], v[190:191]
	v_pk_fma_f32 v[194:195], v[172:173], v[172:173], v[194:195]
	v_lshlrev_b32_e32 v184, 16, v119
	v_and_b32_e32 v185, 0xffff0000, v119
	v_lshlrev_b32_e32 v186, 16, v115
	v_and_b32_e32 v187, 0xffff0000, v115
	v_lshlrev_b32_e32 v188, 16, v111
	v_and_b32_e32 v189, 0xffff0000, v111
	v_lshlrev_b32_e32 v190, 16, v107
	v_and_b32_e32 v191, 0xffff0000, v107
	v_pk_mul_f32 v[192:193], v[8:9], v[184:185]
	v_pk_fma_f32 v[192:193], v[16:17], v[186:187], v[192:193]
	v_pk_fma_f32 v[192:193], v[24:25], v[188:189], v[192:193]
	v_pk_mul_f32 v[174:175], v[192:193], v[190:191]
	v_pk_fma_f32 v[194:195], v[174:175], v[174:175], v[194:195]
	v_add_f32_e32 v48, v194, v195
	v_xor_b32_e32 v56, 32, v208
	v_lshlrev_b32_e32 v56, 2, v56
	v_xor_b32_e32 v57, 16, v208
	v_lshlrev_b32_e32 v57, 2, v57
	v_xor_b32_e32 v58, 8, v208
	v_lshlrev_b32_e32 v58, 2, v58
	v_xor_b32_e32 v59, 4, v208
	v_lshlrev_b32_e32 v59, 2, v59
	v_xor_b32_e32 v60, 2, v208
	v_lshlrev_b32_e32 v60, 2, v60
	v_xor_b32_e32 v61, 1, v208
	v_lshlrev_b32_e32 v61, 2, v61
	v_mov_b32_e32 v62, 0x358637bd
	ds_bpermute_b32 v64, v56, v40
	ds_bpermute_b32 v66, v56, v42
	ds_bpermute_b32 v68, v56, v44
	ds_bpermute_b32 v70, v56, v46
	ds_bpermute_b32 v72, v56, v48
	s_waitcnt lgkmcnt(0)
	v_add_f32_e32 v40, v40, v64
	v_add_f32_e32 v42, v42, v66
	v_add_f32_e32 v44, v44, v68
	v_add_f32_e32 v46, v46, v70
	v_add_f32_e32 v48, v48, v72
	ds_bpermute_b32 v64, v57, v40
	ds_bpermute_b32 v66, v57, v42
	ds_bpermute_b32 v68, v57, v44
	ds_bpermute_b32 v70, v57, v46
	ds_bpermute_b32 v72, v57, v48
	s_waitcnt lgkmcnt(0)
	v_add_f32_e32 v40, v40, v64
	v_add_f32_e32 v42, v42, v66
	v_add_f32_e32 v44, v44, v68
	v_add_f32_e32 v46, v46, v70
	v_add_f32_e32 v48, v48, v72
	ds_bpermute_b32 v64, v58, v40
	ds_bpermute_b32 v66, v58, v42
	ds_bpermute_b32 v68, v58, v44
	ds_bpermute_b32 v70, v58, v46
	ds_bpermute_b32 v72, v58, v48
	s_waitcnt lgkmcnt(0)
	v_add_f32_e32 v40, v40, v64
	v_add_f32_e32 v42, v42, v66
	v_add_f32_e32 v44, v44, v68
	v_add_f32_e32 v46, v46, v70
	v_add_f32_e32 v48, v48, v72
	ds_bpermute_b32 v64, v59, v40
	ds_bpermute_b32 v66, v59, v42
	ds_bpermute_b32 v68, v59, v44
	ds_bpermute_b32 v70, v59, v46
	ds_bpermute_b32 v72, v59, v48
	s_waitcnt lgkmcnt(0)
	v_add_f32_e32 v40, v40, v64
	v_add_f32_e32 v42, v42, v66
	v_add_f32_e32 v44, v44, v68
	v_add_f32_e32 v46, v46, v70
	v_add_f32_e32 v48, v48, v72
	ds_bpermute_b32 v64, v60, v40
	ds_bpermute_b32 v66, v60, v42
	ds_bpermute_b32 v68, v60, v44
	ds_bpermute_b32 v70, v60, v46
	ds_bpermute_b32 v72, v60, v48
	s_waitcnt lgkmcnt(0)
	v_add_f32_e32 v40, v40, v64
	v_add_f32_e32 v42, v42, v66
	v_add_f32_e32 v44, v44, v68
	v_add_f32_e32 v46, v46, v70
	v_add_f32_e32 v48, v48, v72
	ds_bpermute_b32 v64, v61, v40
	ds_bpermute_b32 v66, v61, v42
	ds_bpermute_b32 v68, v61, v44
	ds_bpermute_b32 v70, v61, v46
	ds_bpermute_b32 v72, v61, v48
	s_waitcnt lgkmcnt(0)
; __device__ __forceinline__ unsigned pk2(float lo, float hi) { return pg8::cvt_pk_bf16(lo, hi); }
; template <int NR>
; __device__ __forceinline__ void conv_rows(const Args& a, int r0, int rstride, int lane) {
;     ...
;         s = wave_sum(s); const float rs = rsqrtf(s * (1.f / 512.f) + EPS);
;         v4u o; o.x = pk2(y[0] * rs * ga[0], y[1] * rs * ga[1]); o.y = pk2(y[2] * rs * ga[2], y[3] * rs * ga[3]); o.z = pk2(y[4] * rs * gb[0], y[5] * rs * gb[1]); o.w = pk2(y[6] * rs * gb[2], y[7] * rs * gb[3]);
;         pg8::st_wt16((bf16*)(ws + WS_MIX) + (size_t)row * 1024 + 512 + c0, o); }
	v_add_f32_e32 v40, v40, v64
	v_add_f32_e32 v42, v42, v66
	v_add_f32_e32 v44, v44, v68
	v_add_f32_e32 v46, v46, v70
	v_add_f32_e32 v48, v48, v72
	v_fmamk_f32 v40, v40, 0x3b000000, v62
	v_fmamk_f32 v42, v42, 0x3b000000, v62
	v_fmamk_f32 v44, v44, 0x3b000000, v62
	v_fmamk_f32 v46, v46, 0x3b000000, v62
	v_fmamk_f32 v48, v48, 0x3b000000, v62
	v_rsq_f32_e32 v40, v40
	v_rsq_f32_e32 v42, v42
	v_rsq_f32_e32 v44, v44
	v_rsq_f32_e32 v46, v46
	v_rsq_f32_e32 v48, v48
	s_nop 1
	v_pk_mul_f32 v[184:185], v[136:137], v[40:41] op_sel_hi:[1,0]
	v_pk_mul_f32 v[186:187], v[138:139], v[40:41] op_sel_hi:[1,0]
	v_pk_mul_f32 v[188:189], v[140:141], v[40:41] op_sel_hi:[1,0]
	v_pk_mul_f32 v[190:191], v[142:143], v[40:41] op_sel_hi:[1,0]
	v_pk_mul_f32 v[184:185], v[26:27], v[184:185]
	v_pk_mul_f32 v[186:187], v[28:29], v[186:187]
	v_pk_mul_f32 v[188:189], v[30:31], v[188:189]
	v_pk_mul_f32 v[190:191], v[32:33], v[190:191]
	v_cvt_pk_bf16_f32 v88, v184, v185
	v_cvt_pk_bf16_f32 v89, v186, v187
	v_cvt_pk_bf16_f32 v90, v188, v189
	v_cvt_pk_bf16_f32 v91, v190, v191
	s_add_i32 s10, s24, 0x2400
	s_lshl_b32 s11, s10, 11
	s_add_u32 s4, s26, s11
	s_addc_u32 s5, s27, 0
	global_store_dwordx4 v0, v[88:91], s[4:5] offset:1024
	v_pk_mul_f32 v[184:185], v[144:145], v[42:43] op_sel_hi:[1,0]
	v_pk_mul_f32 v[186:187], v[146:147], v[42:43] op_sel_hi:[1,0]
	v_pk_mul_f32 v[188:189], v[148:149], v[42:43] op_sel_hi:[1,0]
	v_pk_mul_f32 v[190:191], v[150:151], v[42:43] op_sel_hi:[1,0]
	v_pk_mul_f32 v[184:185], v[26:27], v[184:185]
	v_pk_mul_f32 v[186:187], v[28:29], v[186:187]
	v_pk_mul_f32 v[188:189], v[30:31], v[188:189]
	v_pk_mul_f32 v[190:191], v[32:33], v[190:191]
	v_cvt_pk_bf16_f32 v92, v184, v185
	v_cvt_pk_bf16_f32 v93, v186, v187
	v_cvt_pk_bf16_f32 v94, v188, v189
	v_cvt_pk_bf16_f32 v95, v190, v191
	s_add_i32 s10, s24, 0x2a00
	s_lshl_b32 s11, s10, 11
	s_add_u32 s4, s26, s11
	s_addc_u32 s5, s27, 0
	global_store_dwordx4 v0, v[92:95], s[4:5] offset:1024
	v_pk_mul_f32 v[184:185], v[152:153], v[44:45] op_sel_hi:[1,0]
	v_pk_mul_f32 v[186:187], v[154:155], v[44:45] op_sel_hi:[1,0]
	v_pk_mul_f32 v[188:189], v[156:157], v[44:45] op_sel_hi:[1,0]
	v_pk_mul_f32 v[190:191], v[158:159], v[44:45] op_sel_hi:[1,0]
	v_pk_mul_f32 v[184:185], v[26:27], v[184:185]
	v_pk_mul_f32 v[186:187], v[28:29], v[186:187]
	v_pk_mul_f32 v[188:189], v[30:31], v[188:189]
	v_pk_mul_f32 v[190:191], v[32:33], v[190:191]
	v_cvt_pk_bf16_f32 v96, v184, v185
	v_cvt_pk_bf16_f32 v97, v186, v187
	v_cvt_pk_bf16_f32 v98, v188, v189
	v_cvt_pk_bf16_f32 v99, v190, v191
	s_add_i32 s10, s24, 0x3000
	s_lshl_b32 s11, s10, 11
	s_add_u32 s4, s26, s11
	s_addc_u32 s5, s27, 0
	global_store_dwordx4 v0, v[96:99], s[4:5] offset:1024
	v_pk_mul_f32 v[184:185], v[160:161], v[46:47] op_sel_hi:[1,0]
	v_pk_mul_f32 v[186:187], v[162:163], v[46:47] op_sel_hi:[1,0]
	v_pk_mul_f32 v[188:189], v[164:165], v[46:47] op_sel_hi:[1,0]
	v_pk_mul_f32 v[190:191], v[166:167], v[46:47] op_sel_hi:[1,0]
	v_pk_mul_f32 v[184:185], v[26:27], v[184:185]
	v_pk_mul_f32 v[186:187], v[28:29], v[186:187]
	v_pk_mul_f32 v[188:189], v[30:31], v[188:189]
	v_pk_mul_f32 v[190:191], v[32:33], v[190:191]
	v_cvt_pk_bf16_f32 v100, v184, v185
	v_cvt_pk_bf16_f32 v101, v186, v187
	v_cvt_pk_bf16_f32 v102, v188, v189
	v_cvt_pk_bf16_f32 v103, v190, v191
	s_add_i32 s10, s24, 0x3600
	s_lshl_b32 s11, s10, 11
	s_add_u32 s4, s26, s11
	s_addc_u32 s5, s27, 0
	global_store_dwordx4 v0, v[100:103], s[4:5] offset:1024
	v_pk_mul_f32 v[184:185], v[168:169], v[48:49] op_sel_hi:[1,0]
	v_pk_mul_f32 v[186:187], v[170:171], v[48:49] op_sel_hi:[1,0]
	v_pk_mul_f32 v[188:189], v[172:173], v[48:49] op_sel_hi:[1,0]
	v_pk_mul_f32 v[190:191], v[174:175], v[48:49] op_sel_hi:[1,0]
	v_pk_mul_f32 v[184:185], v[26:27], v[184:185]
	v_pk_mul_f32 v[186:187], v[28:29], v[186:187]
	v_pk_mul_f32 v[188:189], v[30:31], v[188:189]
	v_pk_mul_f32 v[190:191], v[32:33], v[190:191]
	v_cvt_pk_bf16_f32 v104, v184, v185
	v_cvt_pk_bf16_f32 v105, v186, v187
	v_cvt_pk_bf16_f32 v106, v188, v189
	v_cvt_pk_bf16_f32 v107, v190, v191
	s_cmpk_lt_u32 s24, 0x400
	s_cbranch_scc0 .Lc5_nostore
	s_add_i32 s10, s24, 0x3c00
	s_lshl_b32 s11, s10, 11
	s_add_u32 s4, s26, s11
	s_addc_u32 s5, s27, 0
	global_store_dwordx4 v0, v[104:107], s[4:5] offset:1024
.Lc5_nostore:
	s_cmp_eq_u64 s[44:45], 0
	s_cbranch_scc1 .Lc5_hgbar
	s_mov_b64 exec, s[44:45]
	v_mov_b32_e32 v0, 0x8900
	s_mov_b32 s10, 0
.Lc5_hgpoll:
	global_load_dword v1, v0, s[46:47] sc1
	s_waitcnt vmcnt(0)
	v_readfirstlane_b32 s11, v1
	s_cmp_ge_u32 s11, 64
	s_cbranch_scc1 .Lc5_hgacq
	s_sleep 1
	s_add_i32 s10, s10, 1
	s_cmp_lt_u32 s10, 20000
	s_cbranch_scc1 .Lc5_hgpoll
.Lc5_hgacq:
	buffer_inv sc1
	s_waitcnt vmcnt(0)
	s_mov_b64 exec, -1
.Lc5_hgbar:
	s_waitcnt lgkmcnt(0)
	s_barrier
	s_load_dwordx4 s[16:19], s[0:1], 0xa8
	s_load_dwordx4 s[12:15], s[0:1], 0x40
	v_lshlrev_b32_e32 v96, 4, v208
	v_mov_b32_e32 v97, 0
	s_waitcnt vmcnt(0) lgkmcnt(0)
	s_branch .LBB0_776
